# stacked: x->bf16 loop loads batched, next-phase weight prefetch by idle barrier waves, TM stage-1 loads reordered with staged waits
# speedup vs baseline: 1.0515x; 1.0026x over previous
; __device__ __forceinline__ unsigned cvt_pk_bf16(float lo, float hi) { unsigned r; asm volatile("v_cvt_pk_bf16_f32 %0, %1, %2" : "=v"(r) : "v"(lo), "v"(hi)); return r; }
;     ...
;     for (int row = gw; row < pg8::MROWS; row += NGW) {
;         const f32x4* xr = (const f32x4*)(x + (size_t)row * 2048) + lane; u32x2* xo = (u32x2*)(XB + (size_t)row * 2048) + lane; float ss = 0.f;
; #pragma unroll
;         for (int j = 0; j < 8; ++j) { const f32x4 v = xr[64 * j]; ss += (v[0] * v[0] + v[1] * v[1]) + (v[2] * v[2] + v[3] * v[3]); u32x2 o; o.x = cvt_pk_bf16(v[0], v[1]); o.y = cvt_pk_bf16(v[2], v[3]); xo[64 * j] = o; }
;         ss = wave_sum(ss); if (lane < 8) SSQ[(size_t)lane * pg8::MROWS + row] = lane == 0 ? ss : 0.f;
;     }
.LBB0_56:
	v_lshl_add_u64 v[22:23], s[92:93], 0, v[6:7]
	v_add_co_u32_e64 v50, s[6:7], s13, v22
	s_waitcnt lgkmcnt(0)
	s_nop 1
	v_addc_co_u32_e64 v51, s[6:7], 0, v23, s[6:7]
	global_load_dwordx4 v[18:21], v[4:5], off offset:-4096
	global_load_dwordx4 v[22:25], v[4:5], off offset:-3072
	global_load_dwordx4 v[26:29], v[4:5], off offset:-2048
	global_load_dwordx4 v[30:33], v[4:5], off offset:-1024
	global_load_dwordx4 v[34:37], v[4:5], off
	global_load_dwordx4 v[38:41], v[4:5], off offset:1024
	global_load_dwordx4 v[42:45], v[4:5], off offset:2048
	global_load_dwordx4 v[46:49], v[4:5], off offset:3072
	s_waitcnt vmcnt(0)
	v_cvt_pk_bf16_f32 v52, v18, v19
	v_cvt_pk_bf16_f32 v53, v20, v21
	global_store_dwordx2 v[50:51], v[52:53], off
	v_cvt_pk_bf16_f32 v54, v22, v23
	v_cvt_pk_bf16_f32 v55, v24, v25
	global_store_dwordx2 v[50:51], v[54:55], off offset:512
	v_cvt_pk_bf16_f32 v56, v26, v27
	v_cvt_pk_bf16_f32 v57, v28, v29
	global_store_dwordx2 v[50:51], v[56:57], off offset:1024
	v_cvt_pk_bf16_f32 v58, v30, v31
	v_cvt_pk_bf16_f32 v59, v32, v33
	global_store_dwordx2 v[50:51], v[58:59], off offset:1536
	v_cvt_pk_bf16_f32 v60, v34, v35
	v_cvt_pk_bf16_f32 v61, v36, v37
	global_store_dwordx2 v[50:51], v[60:61], off offset:2048
	v_cvt_pk_bf16_f32 v62, v38, v39
	v_cvt_pk_bf16_f32 v63, v40, v41
	global_store_dwordx2 v[50:51], v[62:63], off offset:2560
	v_cvt_pk_bf16_f32 v64, v42, v43
	v_cvt_pk_bf16_f32 v65, v44, v45
	global_store_dwordx2 v[50:51], v[64:65], off offset:3072
	v_cmp_lt_i32_e64 s[6:7], v11, v10
	v_mul_f32_e32 v19, v19, v19
	v_mul_f32_e32 v21, v21, v21
	v_fmac_f32_e32 v19, v18, v18
	v_fmac_f32_e32 v21, v20, v20
	v_add_f32_e32 v18, v19, v21
	v_cndmask_b32_e64 v17, v9, v11, s[6:7]
	v_mul_f32_e32 v19, v23, v23
	v_mul_f32_e32 v20, v25, v25
	v_fmac_f32_e32 v19, v22, v22
	v_fmac_f32_e32 v20, v24, v24
	v_add_f32_e32 v19, v19, v20
	v_add_f32_e32 v18, v18, v19
	v_mul_f32_e32 v19, v27, v27
	v_mul_f32_e32 v20, v29, v29
	v_fmac_f32_e32 v19, v26, v26
	v_fmac_f32_e32 v20, v28, v28
	v_add_f32_e32 v19, v19, v20
	v_add_f32_e32 v18, v18, v19
	v_mul_f32_e32 v19, v31, v31
	v_mul_f32_e32 v20, v33, v33
	v_fmac_f32_e32 v19, v30, v30
	v_fmac_f32_e32 v20, v32, v32
	v_add_f32_e32 v19, v19, v20
	v_add_f32_e32 v18, v18, v19
	v_mul_f32_e32 v19, v35, v35
	v_mul_f32_e32 v20, v37, v37
	v_fmac_f32_e32 v19, v34, v34
	v_fmac_f32_e32 v20, v36, v36
	v_add_f32_e32 v19, v19, v20
	v_add_f32_e32 v18, v18, v19
	v_mul_f32_e32 v19, v39, v39
	v_mul_f32_e32 v20, v41, v41
	v_fmac_f32_e32 v19, v38, v38
	v_fmac_f32_e32 v20, v40, v40
	v_add_f32_e32 v19, v19, v20
	v_add_f32_e32 v18, v18, v19
	v_mul_f32_e32 v19, v43, v43
	v_mul_f32_e32 v20, v45, v45
	v_fmac_f32_e32 v19, v42, v42
	v_fmac_f32_e32 v20, v44, v44
	v_add_f32_e32 v19, v19, v20
	v_add_f32_e32 v18, v18, v19
	v_mul_f32_e32 v19, v47, v47
	v_mul_f32_e32 v20, v49, v49
	v_fmac_f32_e32 v19, v46, v46
	v_fmac_f32_e32 v20, v48, v48
	v_add_f32_e32 v19, v19, v20
	v_lshlrev_b32_e32 v17, 2, v17
	v_add_f32_e32 v18, v18, v19
	ds_bpermute_b32 v17, v17, v18
	v_cmp_lt_i32_e64 s[6:7], v12, v10
	v_cvt_pk_bf16_f32 v20, v46, v47
	v_cvt_pk_bf16_f32 v21, v48, v49
	global_store_dwordx2 v[50:51], v[20:21], off offset:3584
	s_waitcnt lgkmcnt(0)
	v_add_f32_e32 v17, v18, v17
	v_cndmask_b32_e64 v19, v9, v12, s[6:7]
	v_lshlrev_b32_e32 v19, 2, v19
	ds_bpermute_b32 v18, v19, v17
	v_cmp_lt_i32_e64 s[6:7], v13, v10
	s_waitcnt lgkmcnt(0)
	v_add_f32_e32 v17, v17, v18
	v_cndmask_b32_e64 v19, v9, v13, s[6:7]
	v_lshlrev_b32_e32 v19, 2, v19
	ds_bpermute_b32 v18, v19, v17
	v_cmp_lt_i32_e64 s[6:7], v14, v10
	s_waitcnt lgkmcnt(0)
	v_add_f32_e32 v17, v17, v18
	v_cndmask_b32_e64 v19, v9, v14, s[6:7]
	v_lshlrev_b32_e32 v19, 2, v19
	ds_bpermute_b32 v18, v19, v17
	v_cmp_lt_i32_e64 s[6:7], v15, v10
	s_waitcnt lgkmcnt(0)
	v_add_f32_e32 v17, v17, v18
	v_cndmask_b32_e64 v19, v9, v15, s[6:7]
	v_lshlrev_b32_e32 v19, 2, v19
	ds_bpermute_b32 v18, v19, v17
	v_cmp_lt_i32_e64 s[6:7], v16, v10
	s_waitcnt lgkmcnt(0)
	v_add_f32_e32 v17, v17, v18
	v_cndmask_b32_e64 v19, v9, v16, s[6:7]
	v_lshlrev_b32_e32 v18, 2, v19
	ds_bpermute_b32 v18, v18, v17
	s_and_saveexec_b64 s[6:7], vcc
	s_cbranch_execz .LBB0_55
	s_waitcnt lgkmcnt(0)
	v_add_f32_e32 v17, v17, v18
	v_cndmask_b32_e64 v17, 0, v17, s[4:5]
	v_lshl_add_u64 v[18:19], s[92:93], 0, v[2:3]
	global_store_dword v[18:19], v17, off
	s_branch .LBB0_55

; __device__ __forceinline__ void xcd_barrier(const XcdBarrier& b) {
;     ...
;     }
;     __syncthreads();
; __global__ void __launch_bounds__(NTHREADS, 2) mk_fwd(Args args) {
;     ...
;             pg8::Gemm g{XB, WIN, XB, WIN, pg8::MROWS, pg8::IN_W, 2048}; pg8::StaticOrder S; S.init(pg8::MROWS, pg8::IN_W, G, blk, 0);
;             pg8::Unit u0; const int pm0 = S.next(0, u0) ? u0.pm : -1;
;             pg8::EpiProj E{PROJ, SSQ + (size_t)(2 * l) * 8 * pg8::MROWS, RS, pm0};
;             pg8::gemm_phase<pg8::EpiProj, pg8::StaticOrder, true, true>(lds, g, S, E);
.LBB0_132:
	s_or_b64 exec, exec, s[4:5]
	v_readfirstlane_b32 vcc_lo, v204
	s_nop 3
	s_lshr_b32 vcc_lo, vcc_lo, 6
	s_cmp_eq_u32 vcc_lo, 0
	s_cbranch_scc1 .Lcv_skip_0
	s_lshr_b32 m0, s85, 5
	v_subrev_u32_e32 v106, 64, v204
	v_mov_b32_e32 v107, m0
	v_lshlrev_b32_e32 v107, 8, v107
	v_mov_b32_e32 v108, v106
	v_lshrrev_b32_e32 v109, 3, v108
	v_add_u32_e32 v109, v109, v107
	v_mul_u32_u24_e32 v109, 0x1000, v109
	v_and_b32_e32 v108, 7, v108
	v_lshl_add_u32 v109, v108, 6, v109
	v_add_u32_e32 v108, 448, v106
	v_lshrrev_b32_e32 v110, 3, v108
	v_add_u32_e32 v110, v110, v107
	v_mul_u32_u24_e32 v110, 0x1000, v110
	v_and_b32_e32 v108, 7, v108
	v_lshl_add_u32 v110, v108, 6, v110
	v_add_u32_e32 v108, 896, v106
	v_lshrrev_b32_e32 v111, 3, v108
	v_add_u32_e32 v111, v111, v107
	v_mul_u32_u24_e32 v111, 0x1000, v111
	v_and_b32_e32 v108, 7, v108
	v_lshl_add_u32 v111, v108, 6, v111
	v_add_u32_e32 v108, 1344, v106
	v_lshrrev_b32_e32 v112, 3, v108
	v_add_u32_e32 v112, v112, v107
	v_mul_u32_u24_e32 v112, 0x1000, v112
	v_and_b32_e32 v108, 7, v108
	v_lshl_add_u32 v112, v108, 6, v112
	v_add_u32_e32 v108, 1792, v106
	v_and_b32_e32 v108, 0x7ff, v108
	v_lshrrev_b32_e32 v113, 3, v108
	v_add_u32_e32 v113, v113, v107
	v_mul_u32_u24_e32 v113, 0x1000, v113
	v_and_b32_e32 v108, 7, v108
	v_lshl_add_u32 v113, v108, 6, v113
	v_readlane_b32 vcc_lo, v250, 36
	v_readlane_b32 vcc_hi, v250, 37
	s_nop 3
	s_add_u32 vcc_lo, vcc_lo, 0x1c0000
	s_addc_u32 vcc_hi, vcc_hi, 0
	global_load_dword v120, v109, vcc
	global_load_dword v121, v110, vcc
	global_load_dword v122, v111, vcc
	global_load_dword v123, v112, vcc
	global_load_dword v124, v113, vcc

; __device__ __forceinline__ void xcd_barrier(const XcdBarrier& b) {
;     ...
;     __syncthreads();
.Lcv_skip_0:
	s_mov_b64 s[4:5], 0
	s_waitcnt lgkmcnt(0)
	s_barrier

; __device__ __forceinline__ unsigned cvt_pk_bf16(float lo, float hi) { unsigned r; asm volatile("v_cvt_pk_bf16_f32 %0, %1, %2" : "=v"(r) : "v"(lo), "v"(hi)); return r; }
; __device__ __forceinline__ void st16_wt(void* p, u32x4 v) { asm volatile("global_store_dwordx4 %0, %1, off sc1\n\ts_nop 1" :: "v"(p), "v"(v) : "memory"); }
; __device__ __forceinline__ void tr_item(const float* __restrict__ W, int K, int N, bf16_t* WT, const float* __restrict__ kscale, int rowmode, int item, int lane) {
;     const int nblk = N >> 5, kb = item / nblk, nb = item - kb * nblk;
;     const int c = lane >> 3, q = lane & 7, k0 = kb * 64 + c * 8, n0 = nb * 32 + q * 4;
;     f32x4 v[8];
; #pragma unroll
;     for (int i = 0; i < 8; ++i) v[i] = __builtin_nontemporal_load((const f32x4*)(W + (size_t)(k0 + i) * N + n0));
;     if (kscale) { const f32x4 s0 = *(const f32x4*)(kscale + k0), s1 = *(const f32x4*)(kscale + k0 + 4);
; #pragma unroll
;         for (int i = 0; i < 4; ++i) { v[i] = v[i] * s0[i]; v[4 + i] = v[4 + i] * s1[i]; } }
;     int drow;
;     if (rowmode == 0) drow = n0;
;     else if (rowmode == 3) { const int g = n0 - pg8::C_GA; drow = g < 0 ? n0 : pg8::C_GA + (((g & 2047) >> 7) << 8) + ((g >> 11) << 7) + (g & 127); }
;     else drow = ((n0 >> 7) << 8) + (n0 & 127) + (rowmode == 2 ? 128 : 0);
; #pragma unroll
;     for (int e = 0; e < 4; ++e) { u32x4 o; o.x = cvt_pk_bf16(v[0][e], v[1][e]); o.y = cvt_pk_bf16(v[2][e], v[3][e]); o.z = cvt_pk_bf16(v[4][e], v[5][e]); o.w = cvt_pk_bf16(v[6][e], v[7][e]);
;         pg8::st16_wt(WT + (size_t)(drow + e) * K + k0, o); }
; __device__ __forceinline__ void xcd_barrier(const XcdBarrier& b) {
;     ...
;     }
;     __syncthreads();
.LBB0_310:
	s_or_b64 exec, exec, s[6:7]
	v_readfirstlane_b32 vcc_lo, v204
	s_nop 3
	s_lshr_b32 vcc_lo, vcc_lo, 6
	s_cmp_eq_u32 vcc_lo, 0
	s_cbranch_scc1 .Lcv_skip_1
	s_cmp_lg_u32 s64, 0
	s_cbranch_scc1 .Lcv_pfwait_1
	v_and_b32_e32 v106, 63, v204
	v_lshrrev_b32_e32 v107, 3, v106
	v_and_b32_e32 v108, 7, v106
	v_readfirstlane_b32 vcc_lo, v204
	s_nop 3
	s_lshr_b32 vcc_lo, vcc_lo, 6
	s_mul_i32 vcc_hi, s85, 7
	s_add_i32 vcc_lo, vcc_lo, vcc_hi
	s_add_i32 vcc_lo, vcc_lo, -1
	s_add_i32 vcc_lo, vcc_lo, 0
	s_sub_u32 vcc_lo, vcc_lo, 0
	v_mov_b32_e32 v113, vcc_lo
	v_mul_u32_u24_e32 v109, 0x5d18, v113
	v_lshrrev_b32_e32 v109, 22, v109
	v_mul_u32_u24_e32 v110, 0xb0, v109
	v_sub_u32_e32 v110, v113, v110
	v_lshlrev_b32_e32 v109, 6, v109
	v_lshl_add_u32 v109, v107, 3, v109
	v_lshlrev_b32_e32 v110, 5, v110
	v_lshl_add_u32 v110, v108, 2, v110
	v_mul_u32_u24_e32 v111, 0x5800, v109
	v_lshl_add_u32 v111, v110, 2, v111
	v_lshrrev_b32_e32 v112, 7, v110
	v_lshlrev_b32_e32 v112, 8, v112
	v_and_b32_e32 v113, 0x7f, v110
	v_add_u32_e32 v112, v112, v113
	v_lshlrev_b32_e32 v112, 12, v112
	v_lshl_add_u32 v112, v109, 1, v112
	v_lshlrev_b32_e32 v113, 2, v109
	v_readlane_b32 vcc_lo, v250, 28
	v_readlane_b32 vcc_hi, v250, 29
	s_nop 4
	global_load_dwordx4 v[98:101], v113, vcc
	global_load_dwordx4 v[102:105], v113, vcc offset:16
	v_readlane_b32 vcc_lo, v250, 30
	v_readlane_b32 vcc_hi, v250, 31
	s_nop 4
	global_load_dwordx4 v[66:69], v111, vcc nt
	v_add_u32_e32 v111, 0x5800, v111
	global_load_dwordx4 v[70:73], v111, vcc nt
	v_add_u32_e32 v111, 0x5800, v111
	global_load_dwordx4 v[74:77], v111, vcc nt
	v_add_u32_e32 v111, 0x5800, v111
	global_load_dwordx4 v[78:81], v111, vcc nt
	v_add_u32_e32 v111, 0x5800, v111
	global_load_dwordx4 v[82:85], v111, vcc nt
	v_add_u32_e32 v111, 0x5800, v111
	global_load_dwordx4 v[86:89], v111, vcc nt
	v_add_u32_e32 v111, 0x5800, v111
	global_load_dwordx4 v[90:93], v111, vcc nt
	v_add_u32_e32 v111, 0x5800, v111
	global_load_dwordx4 v[94:97], v111, vcc nt
	v_readlane_b32 vcc_lo, v250, 36
	v_readlane_b32 vcc_hi, v250, 37
	s_nop 3
	s_add_u32 vcc_lo, vcc_lo, 0x5dc0000
	s_addc_u32 vcc_hi, vcc_hi, 0
	s_waitcnt vmcnt(0)
	v_mul_f32_e32 v66, v66, v98
	v_mul_f32_e32 v67, v67, v98
	v_mul_f32_e32 v68, v68, v98
	v_mul_f32_e32 v69, v69, v98
	v_mul_f32_e32 v70, v70, v99
	v_mul_f32_e32 v71, v71, v99
	v_mul_f32_e32 v72, v72, v99
	v_mul_f32_e32 v73, v73, v99
	v_mul_f32_e32 v74, v74, v100
	v_mul_f32_e32 v75, v75, v100
	v_mul_f32_e32 v76, v76, v100
	v_mul_f32_e32 v77, v77, v100
	v_mul_f32_e32 v78, v78, v101
	v_mul_f32_e32 v79, v79, v101
	v_mul_f32_e32 v80, v80, v101
	v_mul_f32_e32 v81, v81, v101
	v_mul_f32_e32 v82, v82, v102
	v_mul_f32_e32 v83, v83, v102
	v_mul_f32_e32 v84, v84, v102
	v_mul_f32_e32 v85, v85, v102
	v_mul_f32_e32 v86, v86, v103
	v_mul_f32_e32 v87, v87, v103
	v_mul_f32_e32 v88, v88, v103
	v_mul_f32_e32 v89, v89, v103
	v_mul_f32_e32 v90, v90, v104
	v_mul_f32_e32 v91, v91, v104
	v_mul_f32_e32 v92, v92, v104
	v_mul_f32_e32 v93, v93, v104
	v_mul_f32_e32 v94, v94, v105
	v_mul_f32_e32 v95, v95, v105
	v_mul_f32_e32 v96, v96, v105
	v_mul_f32_e32 v97, v97, v105
	v_cvt_pk_bf16_f32 v114, v66, v70
	v_cvt_pk_bf16_f32 v115, v74, v78
	v_cvt_pk_bf16_f32 v116, v82, v86
	v_cvt_pk_bf16_f32 v117, v90, v94
	v_cvt_pk_bf16_f32 v118, v67, v71
	v_cvt_pk_bf16_f32 v119, v75, v79
	v_cvt_pk_bf16_f32 v120, v83, v87
	v_cvt_pk_bf16_f32 v121, v91, v95
	v_cvt_pk_bf16_f32 v122, v68, v72
	v_cvt_pk_bf16_f32 v123, v76, v80
	v_cvt_pk_bf16_f32 v124, v84, v88
	v_cvt_pk_bf16_f32 v125, v92, v96
	v_cvt_pk_bf16_f32 v126, v69, v73
	v_cvt_pk_bf16_f32 v127, v77, v81
	v_cvt_pk_bf16_f32 v128, v85, v89
	v_cvt_pk_bf16_f32 v129, v93, v97
	global_store_dwordx4 v112, v[114:117], vcc sc1
	v_add_u32_e32 v112, 0x1000, v112
	global_store_dwordx4 v112, v[118:121], vcc sc1
	v_add_u32_e32 v112, 0x1000, v112
	global_store_dwordx4 v112, v[122:125], vcc sc1
	v_add_u32_e32 v112, 0x1000, v112
	global_store_dwordx4 v112, v[126:129], vcc sc1
.Lcv_done_1_0:
	s_branch .Lcv_skip_1
.Lcv_pfwait_1:
	s_waitcnt vmcnt(0)
.Lcv_skip_1:
	s_mov_b64 s[6:7], 0
	s_waitcnt lgkmcnt(0)
	s_barrier

; #define LAS __attribute__((address_space(3)))
; __device__ __forceinline__ void p2_block(LAS unsigned char* lds, const bf16_t* __restrict__ PROJ, bf16_t* __restrict__ ATT, bf16_t* __restrict__ SGU, const float* __restrict__ qn, const float* __restrict__ kn, ...
;     ...
;     const int b = item >> 6, n = (item >> 2) & 15, kvh = item & 3;
;     const int lane = tid & 63, w = __builtin_amdgcn_readfirstlane(tid >> 6), fr = lane & 15, fq = lane >> 4;
;     LAS unsigned char* KS = lds; LAS unsigned char* VT = lds + KS_BYTES;
;     const int g = w >> 1, rbase = (w & 1) * 64, hq = kvh * 4 + g;
;     const int kk = tid >> 1, h = tid & 1, s = n * 128 - 128 + kk, sc = s < 0 ? 0 : s;
;     const bf16_t* rowp = PROJ + (size_t)(b * pg8::SEQ + sc) * pg8::IN_W;
;     const bf16_t* kp = rowp + pg8::C_K + kvh * 64 + 16 * h;
;     const u32x4 ka = *(const u32x4*)kp, kb = *(const u32x4*)(kp + 8), kc = *(const u32x4*)(kp + 32), kd = *(const u32x4*)(kp + 40);
;     const bf16_t* vp = rowp + pg8::C_V + kvh * 64 + 32 * h;
;     u32x4 vv[4];
; #pragma unroll
;     for (int c4 = 0; c4 < 4; ++c4) vv[c4] = *(const u32x4*)(vp + 8 * c4);
;     const int sp_ = tid >> 2, q4 = tid & 3;
;     u32x4 sv[2][4];
;     const bf16_t* svsrc = PROJ + ((size_t)b * pg8::SEQ + n * 128 + sp_) * pg8::IN_W + pg8::C_VS + (2 * kvh) * 128 + 32 * q4;
; #pragma unroll
;     for (int c4 = 0; c4 < 4; ++c4) sv[0][c4] = *(const u32x4*)(svsrc + 8 * c4);
;     u32x4 qa[4], qb[4];
; #pragma unroll
;     for (int c = 0; c < 2; ++c) { const bf16_t* qp = PROJ + ((size_t)b * pg8::SEQ + n * 128 + rbase + 16 * c + fr) * pg8::IN_W + hq * 64 + 8 * fq; qa[c] = *(const u32x4*)qp; qb[c] = *(const u32x4*)(qp + 32); }
.LBB0_330:
	s_bfe_u32 s27, s2, 0x40002
	v_mov_b32_e32 v160, v204
	s_lshl_b32 s17, s27, 7
	s_add_i32 s4, s17, 0xffffff80
	v_ashrrev_i32_e32 v167, 1, v160
	v_add_u32_e32 v22, s4, v167
	s_ashr_i32 s6, s2, 6
	v_max_i32_e32 v66, 0, v22
	s_and_b32 s73, s2, 3
	v_lshl_add_u32 v0, s6, 11, v66
	s_waitcnt lgkmcnt(0)
	v_mov_b64_e32 v[2:3], s[10:11]
	v_and_b32_e32 v166, 1, v160
	v_mad_i64_i32 v[4:5], s[24:25], v0, s83, v[2:3]
	s_lshl_b32 s4, s73, 7
	v_lshl_add_u64 v[4:5], v[4:5], 0, s[4:5]
	v_lshlrev_b32_e32 v0, 5, v166
	v_lshl_add_u64 v[6:7], v[4:5], 0, v[0:1]
	global_load_dwordx4 v[50:53], v[6:7], off offset:2048
	global_load_dwordx4 v[58:61], v[6:7], off offset:2064
	global_load_dwordx4 v[54:57], v[6:7], off offset:2112
	global_load_dwordx4 v[62:65], v[6:7], off offset:2128
	v_readfirstlane_b32 s16, v160
	s_ashr_i32 s77, s16, 7
	s_lshl_b32 s7, s73, 2
	s_add_i32 s42, s77, s7
	s_ashr_i32 s7, s6, 31
	v_lshlrev_b32_e32 v74, 6, v166
	v_mov_b32_e32 v75, v1
	v_ashrrev_i32_e32 v136, 2, v160
	s_lshl_b64 s[48:49], s[6:7], 11
	v_lshl_add_u64 v[4:5], v[4:5], 0, v[74:75]
	s_or_b32 s24, s48, s17
	s_mov_b32 s25, s49
	v_ashrrev_i32_e32 v137, 31, v136
	s_waitcnt lgkmcnt(0)
	v_mov_b64_e32 v[144:145], v[4:5]
	s_nop 0
	s_nop 0
	s_nop 0
	v_lshl_add_u64 v[4:5], s[24:25], 0, v[136:137]
	v_mad_u64_u32 v[2:3], s[6:7], v4, s83, v[2:3]
	v_lshlrev_b32_e32 v4, 5, v160
	v_mad_i32_i24 v3, v5, s83, v3
	s_lshl_b32 s4, s73, 9
	v_and_b32_e32 v165, 0x60, v4
	v_lshl_add_u64 v[2:3], v[2:3], 0, s[4:5]
	v_lshlrev_b32_e32 v4, 1, v165
	v_mov_b32_e32 v5, v1
	v_lshl_add_u64 v[2:3], v[2:3], 0, v[4:5]
	s_mov_b64 s[6:7], 0x1400
	v_lshl_add_u64 v[138:139], v[2:3], 0, s[6:7]
	s_lshl_b32 s6, s42, 6
	s_ashr_i32 s7, s6, 31
	s_and_b32 s26, s16, 64
	s_lshl_b64 s[6:7], s[6:7], 1
	v_bfe_u32 v162, v160, 4, 2
	s_add_u32 s28, s10, s6
	s_movk_i32 s4, 0x1000
	v_and_b32_e32 v137, 15, v160
	s_addc_u32 s29, s11, s7
	v_lshlrev_b32_e32 v132, 4, v162
	v_mov_b32_e32 v133, v1
	v_and_b32_e32 v68, 64, v211
	v_add_co_u32_e32 v2, vcc, s4, v2
	v_or_b32_e32 v161, s26, v137
	v_lshl_add_u64 v[134:135], s[28:29], 0, v[132:133]
	v_xor_b32_e32 v67, 1, v211
	v_add_u32_e32 v133, 64, v68
	v_addc_co_u32_e32 v3, vcc, 0, v3, vcc
	v_or_b32_e32 v163, s24, v161
	v_cmp_lt_i32_e64 s[40:41], v67, v133
	v_cmp_gt_i32_e32 vcc, 0, v22
	v_mad_u64_u32 v[22:23], s[28:29], v163, s83, v[134:135]
	v_cndmask_b32_e64 v67, v211, v67, s[40:41]
	v_mad_i32_i24 v23, s49, v212, v23
	v_lshlrev_b32_e32 v164, 2, v67
	v_lshlrev_b32_e32 v66, 5, v66
	v_mov_b32_e32 v67, v1
	v_readlane_b32 s44, v250, 36
	v_readlane_b32 s46, v250, 38
	s_nop 0
	s_nop 0
	s_nop 0
	s_nop 0
	s_nop 0
	v_or_b32_e32 v22, 16, v163
	v_lshlrev_b64 v[66:67], 2, v[66:67]
	v_readlane_b32 s45, v250, 37
	v_readlane_b32 s47, v250, 39
	v_mad_u64_u32 v[26:27], s[28:29], v22, s83, v[134:135]
	v_lshl_add_u64 v[68:69], s[44:45], 0, v[66:67]
	v_lshl_add_u64 v[66:67], s[46:47], 0, v[66:67]
	v_mad_i32_i24 v27, s49, v212, v27
	v_lshl_add_u64 v[86:87], v[68:69], 0, v[74:75]
	v_lshl_add_u64 v[126:127], v[66:67], 0, v[74:75]
	s_nop 0
	s_nop 0
	global_load_dwordx4 v[66:69], v74, s[0:1] offset:48
	global_load_dwordx4 v[78:81], v74, s[0:1] offset:32
	global_load_dwordx4 v[94:97], v74, s[0:1] offset:16
	global_load_dwordx4 v[106:109], v74, s[0:1]
	global_load_dwordx4 v[70:73], v74, s[0:1] offset:176
	global_load_dwordx4 v[82:85], v74, s[0:1] offset:160
	global_load_dwordx4 v[98:101], v74, s[0:1] offset:144
	global_load_dwordx4 v[110:113], v74, s[0:1] offset:128
	s_nop 0
	global_load_dwordx4 v[74:77], v[86:87], off offset:48
	global_load_dwordx4 v[90:93], v[86:87], off offset:32
	global_load_dwordx4 v[102:105], v[86:87], off offset:16
	global_load_dwordx4 v[114:117], v[86:87], off
	s_nop 0
	global_load_dwordx4 v[86:89], v[126:127], off offset:48
	global_load_dwordx4 v[118:121], v[126:127], off offset:32
	global_load_dwordx4 v[122:125], v[126:127], off offset:16
	s_nop 0
	global_load_dwordx4 v[126:129], v[126:127], off
	v_cndmask_b32_e64 v180, 1.0, 0, vcc
	s_lshl_b32 s4, s73, 10
	global_load_dwordx4 v[46:49], v[2:3], off offset:1024
	global_load_dwordx4 v[34:37], v[138:139], off offset:48
	global_load_dwordx4 v[38:41], v[138:139], off offset:32
	global_load_dwordx4 v[42:45], v[138:139], off offset:16
	global_load_dwordx4 v[18:21], v[144:145], off offset:2560
	global_load_dwordx4 v[14:17], v[144:145], off offset:2576
	global_load_dwordx4 v[10:13], v[144:145], off offset:2592
	global_load_dwordx4 v[6:9], v[144:145], off offset:2608
	s_waitcnt vmcnt(8)
; __device__ __forceinline__ void unpack8(const u32x4 w, float* f) { f[0] = bf_lo(w.x); f[1] = bf_hi(w.x); f[2] = bf_lo(w.y); f[3] = bf_hi(w.y); f[4] = bf_lo(w.z); f[5] = bf_hi(w.z); f[6] = bf_lo(w.w); f[7] = bf_hi(w.w); }
; __device__ __forceinline__ void p2_block(LAS unsigned char* lds, const bf16_t* __restrict__ PROJ, bf16_t* __restrict__ ATT, bf16_t* __restrict__ SGU, const float* __restrict__ qn, const float* __restrict__ kn, ...
;     ...
;         const float valid = s < 0 ? 0.f : 1.f;
;         float x1[16], x2[16]; unpack8(ka, x1); unpack8(kb, x1 + 8); unpack8(kc, x2); unpack8(kd, x2 + 8);
;         float ss = 0.f;
; #pragma unroll
;         for (int j = 0; j < 16; ++j) ss += x1[j] * x1[j] + x2[j] * x2[j];
;         ss += __shfl_xor(ss, 1);
;         const float rinv = rsqrtf(ss * (1.0f / 64.0f) + pg8::EPS) * valid;
;         const float* cp = COS + sc * 32 + 16 * h; const float* sp = SIN + sc * 32 + 16 * h;
;         float o1[16], o2[16];
; #pragma unroll
;         for (int j = 0; j < 16; ++j) { const float a1 = x1[j] * rinv * kn[16 * h + j], a2 = x2[j] * rinv * kn[32 + 16 * h + j], c = cp[j], sn = sp[j]; o1[j] = a1 * c - a2 * sn; o2[j] = a2 * c + a1 * sn; }
	v_lshlrev_b32_e32 v226, 16, v51
	v_lshlrev_b32_e32 v142, 16, v61
	v_and_b32_e32 v140, 0xffff0000, v61
	v_lshlrev_b32_e32 v143, 16, v65
	v_and_b32_e32 v141, 0xffff0000, v65
	v_mov_b32_e32 v150, v141
	v_mov_b32_e32 v151, v143
	v_mov_b32_e32 v148, v140
	v_mov_b32_e32 v149, v142
	v_pk_mul_f32 v[150:151], v[150:151], v[150:151]
	v_and_b32_e32 v61, 0xffff0000, v64
	v_pk_fma_f32 v[182:183], v[148:149], v[148:149], v[150:151]
	v_lshlrev_b32_e32 v149, 16, v64
	v_lshlrev_b32_e32 v148, 16, v60
	v_and_b32_e32 v60, 0xffff0000, v60
	v_mov_b32_e32 v154, v61
	v_mov_b32_e32 v155, v149
	v_mov_b32_e32 v64, v60
	v_mov_b32_e32 v65, v148
	v_pk_mul_f32 v[154:155], v[154:155], v[154:155]
	v_and_b32_e32 v201, 0xffff0000, v57
	v_pk_fma_f32 v[184:185], v[64:65], v[64:65], v[154:155]
	v_lshlrev_b32_e32 v155, 16, v63
	v_and_b32_e32 v65, 0xffff0000, v63
	v_lshlrev_b32_e32 v154, 16, v59
	v_and_b32_e32 v64, 0xffff0000, v59
	v_mov_b32_e32 v188, v65
	v_mov_b32_e32 v189, v155
	v_mov_b32_e32 v186, v64
	v_mov_b32_e32 v187, v154
	v_pk_mul_f32 v[188:189], v[188:189], v[188:189]
	v_and_b32_e32 v59, 0xffff0000, v62
	v_pk_fma_f32 v[186:187], v[186:187], v[186:187], v[188:189]
	v_lshlrev_b32_e32 v189, 16, v62
	v_lshlrev_b32_e32 v188, 16, v58
	v_and_b32_e32 v58, 0xffff0000, v58
	v_mov_b32_e32 v194, v59
	v_mov_b32_e32 v195, v189
	v_mov_b32_e32 v62, v58
	v_mov_b32_e32 v63, v188
	v_pk_mul_f32 v[194:195], v[194:195], v[194:195]
	v_and_b32_e32 v234, 0xffff0000, v51
	v_pk_fma_f32 v[62:63], v[62:63], v[62:63], v[194:195]
	v_lshlrev_b32_e32 v195, 16, v57
	v_lshlrev_b32_e32 v239, 16, v54
	v_lshlrev_b32_e32 v238, 16, v50
	v_and_b32_e32 v51, 0xffff0000, v54
	v_and_b32_e32 v50, 0xffff0000, v50
	v_lshlrev_b32_e32 v194, 16, v53
	v_and_b32_e32 v200, 0xffff0000, v53
	v_mov_b32_e32 v218, v201
	v_mov_b32_e32 v219, v195
	v_lshlrev_b32_e32 v227, 16, v55
	v_and_b32_e32 v235, 0xffff0000, v55
	v_pk_mul_f32 v[240:241], v[238:239], v[238:239]
	v_pk_mul_f32 v[54:55], v[50:51], v[50:51]
	v_mov_b32_e32 v202, v200
	v_mov_b32_e32 v203, v194
	v_pk_mul_f32 v[218:219], v[218:219], v[218:219]
	v_pk_mul_f32 v[228:229], v[226:227], v[226:227]
	v_add_f32_e32 v54, v54, v55
	v_add_f32_e32 v55, v240, v241
	v_pk_fma_f32 v[202:203], v[202:203], v[202:203], v[218:219]
	v_lshlrev_b32_e32 v219, 16, v56
	v_lshlrev_b32_e32 v218, 16, v52
	v_pk_mul_f32 v[236:237], v[234:235], v[234:235]
	v_add_f32_e32 v54, v55, v54
	v_add_f32_e32 v55, v228, v229
	v_mov_b32_e32 v150, v66
	v_pk_mul_f32 v[220:221], v[218:219], v[218:219]
	v_and_b32_e32 v53, 0xffff0000, v56
	v_and_b32_e32 v52, 0xffff0000, v52
	v_add_f32_e32 v66, v236, v237
	v_add_f32_e32 v54, v55, v54
	v_pk_mul_f32 v[56:57], v[52:53], v[52:53]
	v_add_f32_e32 v54, v66, v54
	v_add_f32_e32 v55, v220, v221
	v_add_f32_e32 v54, v55, v54
	v_add_f32_e32 v55, v56, v57
	v_add_f32_e32 v54, v55, v54
	v_add_f32_e32 v54, v203, v54
	v_add_f32_e32 v54, v202, v54
	v_add_f32_e32 v54, v63, v54
	v_add_f32_e32 v54, v62, v54
	v_add_f32_e32 v54, v187, v54
	v_add_f32_e32 v54, v186, v54
	v_add_f32_e32 v54, v185, v54
	v_add_f32_e32 v54, v184, v54
	v_add_f32_e32 v54, v183, v54
	v_add_f32_e32 v54, v182, v54
	s_nop 1
	v_mov_b32_dpp v55, v54 quad_perm:[1,0,3,2] row_mask:0xf bank_mask:0xf
	v_mov_b32_e32 v242, v106
	v_mov_b32_e32 v243, v110
	v_mov_b32_e32 v244, v114
	v_mov_b32_e32 v245, v126
	s_waitcnt lgkmcnt(0)
	v_add_f32_e32 v54, v54, v55
	v_fmamk_f32 v54, v54, 0x3c800000, v209
	v_cmp_gt_f32_e64 s[40:41], s82, v54
	v_mul_f32_e32 v55, 0x4b800000, v54
	v_mov_b32_e32 v110, v107
	v_cndmask_b32_e64 v54, v54, v55, s[40:41]
	v_rsq_f32_e32 v54, v54
	v_mov_b32_e32 v230, v108
	v_mov_b32_e32 v231, v112
	v_mov_b32_e32 v232, v116
	v_mul_f32_e32 v55, 0x45800000, v54
	v_cndmask_b32_e64 v54, v54, v55, s[40:41]
	v_mul_f32_e32 v54, v180, v54
	v_pk_mul_f32 v[56:57], v[54:55], v[238:239] op_sel_hi:[0,1]
	v_pk_mul_f32 v[56:57], v[242:243], v[56:57]
	v_mov_b32_e32 v233, v128
	v_pk_mul_f32 v[62:63], v[244:245], v[56:57]
	v_mov_b32_e32 v144, v68
	v_sub_f32_e32 v55, v62, v63
	v_mov_b32_e32 v62, v126
	v_mov_b32_e32 v63, v114
	v_pk_mul_f32 v[50:51], v[54:55], v[50:51] op_sel_hi:[0,1]
	v_pk_mul_f32 v[56:57], v[62:63], v[56:57]
	v_pk_mul_f32 v[50:51], v[110:111], v[50:51]
	v_mov_b32_e32 v126, v115
	v_mov_b32_e32 v114, v127
	v_add_f32_e32 v62, v57, v56
	v_pk_mul_f32 v[56:57], v[126:127], v[50:51]
	v_pk_mul_f32 v[50:51], v[114:115], v[50:51]
	v_sub_f32_e32 v63, v56, v57
	v_add_f32_e32 v66, v51, v50
	v_pk_mul_f32 v[50:51], v[54:55], v[226:227] op_sel_hi:[0,1]
	v_pk_mul_f32 v[50:51], v[230:231], v[50:51]
	v_mov_b32_e32 v190, v78
	v_pk_mul_f32 v[56:57], v[232:233], v[50:51]
	v_mov_b32_e32 v112, v109
	v_sub_f32_e32 v68, v56, v57
	v_mov_b32_e32 v56, v128
	v_mov_b32_e32 v57, v116
	v_pk_mul_f32 v[50:51], v[56:57], v[50:51]
	v_mov_b32_e32 v128, v117
	v_add_f32_e32 v78, v51, v50
	v_pk_mul_f32 v[50:51], v[54:55], v[234:235] op_sel_hi:[0,1]
	v_pk_mul_f32 v[50:51], v[112:113], v[50:51]
	v_mov_b32_e32 v116, v129
	v_pk_mul_f32 v[56:57], v[128:129], v[50:51]
	v_pk_mul_f32 v[50:51], v[116:117], v[50:51]
	v_mov_b32_e32 v222, v94
	v_mov_b32_e32 v223, v98
	v_add_f32_e32 v94, v51, v50
	v_pk_mul_f32 v[50:51], v[54:55], v[218:219] op_sel_hi:[0,1]
	v_mov_b32_e32 v224, v102
	v_mov_b32_e32 v225, v122
	v_pk_mul_f32 v[50:51], v[50:51], v[222:223]
	v_mov_b32_e32 v156, v80
	v_sub_f32_e32 v80, v56, v57
	v_pk_mul_f32 v[56:57], v[50:51], v[224:225]
	v_mov_b32_e32 v196, v96
	v_sub_f32_e32 v96, v56, v57
	v_mov_b32_e32 v56, v122
	v_mov_b32_e32 v57, v102
	v_pk_mul_f32 v[50:51], v[50:51], v[56:57]
	v_mov_b32_e32 v98, v95
	v_add_f32_e32 v106, v51, v50
	v_pk_mul_f32 v[50:51], v[54:55], v[52:53] op_sel_hi:[0,1]
	v_pk_mul_f32 v[50:51], v[50:51], v[98:99]
	v_mov_b32_e32 v122, v103
; __device__ __forceinline__ unsigned cvt_pk_bf16(float lo, float hi) { unsigned r; asm volatile("v_cvt_pk_bf16_f32 %0, %1, %2" : "=v"(r) : "v"(lo), "v"(hi)); return r; }
; #define LAS __attribute__((address_space(3)))
; __device__ __forceinline__ void p2_block(LAS unsigned char* lds, const bf16_t* __restrict__ PROJ, bf16_t* __restrict__ ATT, bf16_t* __restrict__ SGU, const float* __restrict__ qn, const float* __restrict__ kn, ...
;     ...
;         for (int j = 0; j < 16; ++j) { const float a1 = x1[j] * rinv * kn[16 * h + j], a2 = x2[j] * rinv * kn[32 + 16 * h + j], c = cp[j], sn = sp[j]; o1[j] = a1 * c - a2 * sn; o2[j] = a2 * c + a1 * sn; }
;         LAS unsigned char* kdst = KS + kk * KS_STRIDE + 32 * h;
;         u32x4 w0, w1;
;         w0.x = cvt_pk_bf16(o1[0], o1[1]); w0.y = cvt_pk_bf16(o1[2], o1[3]); w0.z = cvt_pk_bf16(o1[4], o1[5]); w0.w = cvt_pk_bf16(o1[6], o1[7]);
;         w1.x = cvt_pk_bf16(o1[8], o1[9]); w1.y = cvt_pk_bf16(o1[10], o1[11]); w1.z = cvt_pk_bf16(o1[12], o1[13]); w1.w = cvt_pk_bf16(o1[14], o1[15]);
;         *(LAS u32x4*)kdst = w0; *(LAS u32x4*)(kdst + 16) = w1;
;         w0.x = cvt_pk_bf16(o2[0], o2[1]); w0.y = cvt_pk_bf16(o2[2], o2[3]); w0.z = cvt_pk_bf16(o2[4], o2[5]); w0.w = cvt_pk_bf16(o2[6], o2[7]);
;         w1.x = cvt_pk_bf16(o2[8], o2[9]); w1.y = cvt_pk_bf16(o2[10], o2[11]); w1.z = cvt_pk_bf16(o2[12], o2[13]); w1.w = cvt_pk_bf16(o2[14], o2[15]);
;         *(LAS u32x4*)(kdst + 64) = w0; *(LAS u32x4*)(kdst + 80) = w1;
;     ...
;         const float* gp = lng + gg * 128 + 32 * q4; const float* bp = lnb + gg * 128 + 32 * q4;
	v_mov_b32_e32 v102, v123
	v_pk_mul_f32 v[52:53], v[50:51], v[122:123]
	v_pk_mul_f32 v[50:51], v[50:51], v[102:103]
	v_mov_b32_e32 v197, v100
	v_add_f32_e32 v95, v51, v50
	v_pk_mul_f32 v[50:51], v[54:55], v[194:195] op_sel_hi:[0,1]
	v_mov_b32_e32 v198, v104
	v_mov_b32_e32 v199, v124
	v_pk_mul_f32 v[50:51], v[50:51], v[196:197]
	v_sub_f32_e32 v56, v52, v53
	v_pk_mul_f32 v[52:53], v[50:51], v[198:199]
	v_mov_b32_e32 v100, v97
	v_sub_f32_e32 v57, v52, v53
	v_mov_b32_e32 v52, v124
	v_mov_b32_e32 v53, v104
	v_pk_mul_f32 v[50:51], v[50:51], v[52:53]
	v_mov_b32_e32 v124, v105
	v_add_f32_e32 v98, v51, v50
	v_pk_mul_f32 v[50:51], v[54:55], v[200:201] op_sel_hi:[0,1]
	v_pk_mul_f32 v[50:51], v[50:51], v[100:101]
	v_mov_b32_e32 v104, v125
	v_pk_mul_f32 v[52:53], v[50:51], v[124:125]
	v_pk_mul_f32 v[50:51], v[50:51], v[104:105]
	v_mov_b32_e32 v191, v82
	v_add_f32_e32 v99, v51, v50
	v_pk_mul_f32 v[50:51], v[54:55], v[188:189] op_sel_hi:[0,1]
	v_mov_b32_e32 v192, v90
	v_mov_b32_e32 v193, v118
	v_pk_mul_f32 v[50:51], v[50:51], v[190:191]
	v_sub_f32_e32 v97, v52, v53
	v_pk_mul_f32 v[52:53], v[50:51], v[192:193]
	v_mov_b32_e32 v82, v79
	v_sub_f32_e32 v100, v52, v53
	v_mov_b32_e32 v52, v118
	v_mov_b32_e32 v53, v90
	v_pk_mul_f32 v[50:51], v[50:51], v[52:53]
	v_mov_b32_e32 v118, v91
	v_add_f32_e32 v101, v51, v50
	v_pk_mul_f32 v[50:51], v[54:55], v[58:59] op_sel_hi:[0,1]
	v_pk_mul_f32 v[50:51], v[50:51], v[82:83]
	v_mov_b32_e32 v90, v119
	v_pk_mul_f32 v[52:53], v[50:51], v[118:119]
	v_pk_mul_f32 v[50:51], v[50:51], v[90:91]
	v_mov_b32_e32 v157, v84
	v_add_f32_e32 v59, v51, v50
	v_pk_mul_f32 v[50:51], v[54:55], v[154:155] op_sel_hi:[0,1]
	v_mov_b32_e32 v158, v92
	v_mov_b32_e32 v159, v120
	v_pk_mul_f32 v[50:51], v[50:51], v[156:157]
	v_sub_f32_e32 v58, v52, v53
	v_pk_mul_f32 v[52:53], v[50:51], v[158:159]
	v_mov_b32_e32 v84, v81
	v_sub_f32_e32 v79, v52, v53
	v_mov_b32_e32 v52, v120
	v_mov_b32_e32 v53, v92
	v_pk_mul_f32 v[50:51], v[50:51], v[52:53]
	v_mov_b32_e32 v120, v93
	v_add_f32_e32 v82, v51, v50
	v_pk_mul_f32 v[50:51], v[54:55], v[64:65] op_sel_hi:[0,1]
	v_pk_mul_f32 v[50:51], v[50:51], v[84:85]
	v_mov_b32_e32 v92, v121
	v_pk_mul_f32 v[52:53], v[50:51], v[120:121]
	v_pk_mul_f32 v[50:51], v[50:51], v[92:93]
	v_mov_b32_e32 v151, v70
	v_add_f32_e32 v65, v51, v50
	v_pk_mul_f32 v[50:51], v[54:55], v[148:149] op_sel_hi:[0,1]
	v_mov_b32_e32 v152, v74
	v_mov_b32_e32 v153, v86
	v_pk_mul_f32 v[50:51], v[50:51], v[150:151]
	v_sub_f32_e32 v64, v52, v53
	v_pk_mul_f32 v[52:53], v[50:51], v[152:153]
	v_mov_b32_e32 v70, v67
	v_sub_f32_e32 v81, v52, v53
	v_mov_b32_e32 v52, v86
	v_mov_b32_e32 v53, v74
	v_pk_mul_f32 v[50:51], v[50:51], v[52:53]
	v_mov_b32_e32 v86, v75
	v_add_f32_e32 v83, v51, v50
	v_pk_mul_f32 v[50:51], v[54:55], v[60:61] op_sel_hi:[0,1]
	v_pk_mul_f32 v[50:51], v[50:51], v[70:71]
	v_mov_b32_e32 v74, v87
	v_pk_mul_f32 v[52:53], v[50:51], v[86:87]
	v_pk_mul_f32 v[50:51], v[50:51], v[74:75]
	v_mov_b32_e32 v145, v72
	v_add_f32_e32 v61, v51, v50
	v_pk_mul_f32 v[50:51], v[54:55], v[142:143] op_sel_hi:[0,1]
	v_mov_b32_e32 v146, v76
	v_mov_b32_e32 v147, v88
	v_pk_mul_f32 v[50:51], v[50:51], v[144:145]
	v_sub_f32_e32 v60, v52, v53
	v_pk_mul_f32 v[52:53], v[50:51], v[146:147]
	v_mov_b32_e32 v72, v69
	v_lshl_add_u32 v182, v165, 2, s4
	global_load_dwordx4 v[144:147], v182, s[36:37] offset:0
	global_load_dwordx4 v[148:151], v182, s[36:37] offset:16
	global_load_dwordx4 v[152:155], v182, s[36:37] offset:32
	global_load_dwordx4 v[156:159], v182, s[36:37] offset:48
	global_load_dwordx4 v[184:187], v182, s[36:37] offset:64
	global_load_dwordx4 v[188:191], v182, s[36:37] offset:80
	global_load_dwordx4 v[192:195], v182, s[36:37] offset:96
	global_load_dwordx4 v[196:199], v182, s[36:37] offset:112
	global_load_dwordx4 v[218:221], v182, s[18:19] offset:0
	global_load_dwordx4 v[222:225], v182, s[18:19] offset:16
	global_load_dwordx4 v[226:229], v182, s[18:19] offset:32
	global_load_dwordx4 v[230:233], v182, s[18:19] offset:48
	global_load_dwordx4 v[234:237], v182, s[18:19] offset:64
	global_load_dwordx4 v[238:241], v182, s[18:19] offset:80
	global_load_dwordx4 v[242:245], v182, s[18:19] offset:96
	global_load_dwordx4 v[200:203], v182, s[18:19] offset:112
	v_sub_f32_e32 v67, v52, v53
	v_mov_b32_e32 v52, v88
	v_mov_b32_e32 v53, v76
	v_pk_mul_f32 v[50:51], v[50:51], v[52:53]
	v_mov_b32_e32 v88, v77
	v_add_f32_e32 v70, v51, v50
	v_pk_mul_f32 v[50:51], v[54:55], v[140:141] op_sel_hi:[0,1]
	v_pk_mul_f32 v[50:51], v[50:51], v[72:73]
	v_mov_b32_e32 v76, v89
	v_pk_mul_f32 v[52:53], v[50:51], v[88:89]
	v_pk_mul_f32 v[50:51], v[50:51], v[76:77]
	v_sub_f32_e32 v69, v52, v53
	v_add_f32_e32 v71, v51, v50
	v_mul_lo_u32 v50, v167, s59
	v_add3_u32 v0, 0, v50, v0
	v_cvt_pk_bf16_f32 v50, v55, v63
	v_cvt_pk_bf16_f32 v51, v68, v80
	v_cvt_pk_bf16_f32 v52, v96, v56
	v_cvt_pk_bf16_f32 v53, v57, v97
	v_cvt_pk_bf16_f32 v54, v100, v58
	v_cvt_pk_bf16_f32 v55, v79, v64
	v_cvt_pk_bf16_f32 v56, v81, v60
	v_cvt_pk_bf16_f32 v57, v67, v69
	s_waitcnt vmcnt(20)
; __device__ __forceinline__ unsigned cvt_pk_bf16(float lo, float hi) { unsigned r; asm volatile("v_cvt_pk_bf16_f32 %0, %1, %2" : "=v"(r) : "v"(lo), "v"(hi)); return r; }
; __device__ __forceinline__ float gelu_f(float x) { const float y2 = 1.5957691216057308f * x * (1.0f + 0.044715f * x * x); return x * sigmoid_f(y2); }
; #define LAS __attribute__((address_space(3)))
; __device__ __forceinline__ void unpack8(const u32x4 w, float* f) { f[0] = bf_lo(w.x); f[1] = bf_hi(w.x); f[2] = bf_lo(w.y); f[3] = bf_hi(w.y); f[4] = bf_lo(w.z); f[5] = bf_hi(w.z); f[6] = bf_lo(w.w); f[7] = bf_hi(w.w); }
; __device__ __forceinline__ void p2_block(LAS unsigned char* lds, const bf16_t* __restrict__ PROJ, bf16_t* __restrict__ ATT, bf16_t* __restrict__ SGU, const float* __restrict__ qn, const float* __restrict__ kn, ...
;     ...
;         LAS unsigned char* kdst = KS + kk * KS_STRIDE + 32 * h;
;         u32x4 w0, w1;
;         w0.x = cvt_pk_bf16(o1[0], o1[1]); w0.y = cvt_pk_bf16(o1[2], o1[3]); w0.z = cvt_pk_bf16(o1[4], o1[5]); w0.w = cvt_pk_bf16(o1[6], o1[7]);
;         w1.x = cvt_pk_bf16(o1[8], o1[9]); w1.y = cvt_pk_bf16(o1[10], o1[11]); w1.z = cvt_pk_bf16(o1[12], o1[13]); w1.w = cvt_pk_bf16(o1[14], o1[15]);
;         *(LAS u32x4*)kdst = w0; *(LAS u32x4*)(kdst + 16) = w1;
;         w0.x = cvt_pk_bf16(o2[0], o2[1]); w0.y = cvt_pk_bf16(o2[2], o2[3]); w0.z = cvt_pk_bf16(o2[4], o2[5]); w0.w = cvt_pk_bf16(o2[6], o2[7]);
;         w1.x = cvt_pk_bf16(o2[8], o2[9]); w1.y = cvt_pk_bf16(o2[10], o2[11]); w1.z = cvt_pk_bf16(o2[12], o2[13]); w1.w = cvt_pk_bf16(o2[14], o2[15]);
;         *(LAS u32x4*)(kdst + 64) = w0; *(LAS u32x4*)(kdst + 80) = w1;
;     ...
;         float v[32];
; #pragma unroll
;         for (int c4 = 0; c4 < 4; ++c4) unpack8(sv[gi][c4], v + 8 * c4);
;         float sm = 0.f;
; #pragma unroll
;         for (int j = 0; j < 32; ++j) { v[j] = gelu_f(v[j]); sm += v[j]; }
	v_lshlrev_b32_e32 v73, 16, v46
	ds_write_b128 v0, v[50:53]
	ds_write_b128 v0, v[54:57] offset:16
	v_cvt_pk_bf16_f32 v50, v62, v66
	v_cvt_pk_bf16_f32 v51, v78, v94
	v_cvt_pk_bf16_f32 v52, v106, v95
	v_cvt_pk_bf16_f32 v53, v98, v99
	v_cvt_pk_bf16_f32 v54, v101, v59
	v_cvt_pk_bf16_f32 v55, v82, v65
	v_cvt_pk_bf16_f32 v56, v83, v61
	v_cvt_pk_bf16_f32 v57, v70, v71
	v_lshlrev_b32_e32 v70, 16, v48
	v_and_b32_e32 v69, 0xffff0000, v48
	v_lshlrev_b32_e32 v68, 16, v49
	v_and_b32_e32 v67, 0xffff0000, v49
	v_lshlrev_b32_e32 v66, 16, v42
	v_and_b32_e32 v65, 0xffff0000, v42
	v_lshlrev_b32_e32 v64, 16, v43
	v_and_b32_e32 v63, 0xffff0000, v43
	v_lshlrev_b32_e32 v62, 16, v44
	v_and_b32_e32 v61, 0xffff0000, v44
	v_lshlrev_b32_e32 v60, 16, v45
	v_and_b32_e32 v59, 0xffff0000, v45
	v_lshlrev_b32_e32 v49, 16, v40
	v_and_b32_e32 v48, 0xffff0000, v40
	v_lshlrev_b32_e32 v45, 16, v41
	v_and_b32_e32 v44, 0xffff0000, v41
	v_lshlrev_b32_e32 v43, 16, v34
	v_and_b32_e32 v42, 0xffff0000, v34
	v_lshlrev_b32_e32 v41, 16, v35
	v_and_b32_e32 v40, 0xffff0000, v35
	v_lshlrev_b32_e32 v35, 16, v37
	v_and_b32_e32 v34, 0xffff0000, v37
	v_mul_f32_e32 v37, 0x3d372713, v73
	ds_write_b128 v0, v[50:53] offset:64
	ds_write_b128 v0, v[54:57] offset:80
	v_lshlrev_b32_e32 v58, 16, v38
	v_and_b32_e32 v57, 0xffff0000, v38
	v_lshlrev_b32_e32 v56, 16, v39
	v_and_b32_e32 v55, 0xffff0000, v39
	v_lshlrev_b32_e32 v39, 16, v36
	v_and_b32_e32 v38, 0xffff0000, v36
	v_mul_f32_e32 v36, 0x3fcc422a, v73
	v_fma_f32 v37, v37, v73, 1.0
	v_mul_f32_e32 v36, v36, v37
	v_mul_f32_e32 v36, 0xbfb8aa3b, v36
	v_exp_f32_e32 v36, v36
	v_and_b32_e32 v74, 0xffff0000, v46
	v_mul_f32_e32 v37, 0x3d372713, v74
	v_fma_f32 v37, v37, v74, 1.0
	v_add_f32_e32 v36, 1.0, v36
	v_rcp_f32_e32 v75, v36
	v_mul_f32_e32 v36, 0x3fcc422a, v74
	v_mul_f32_e32 v36, v36, v37
	v_mul_f32_e32 v36, 0xbfb8aa3b, v36
	v_exp_f32_e32 v36, v36
	v_lshlrev_b32_e32 v72, 16, v47
	v_mul_f32_e32 v37, 0x3d372713, v72
	v_fma_f32 v37, v37, v72, 1.0
	v_add_f32_e32 v36, 1.0, v36
	v_rcp_f32_e32 v76, v36
	v_mul_f32_e32 v36, 0x3fcc422a, v72
	v_mul_f32_e32 v36, v36, v37
	v_mul_f32_e32 v36, 0xbfb8aa3b, v36
	v_exp_f32_e32 v36, v36
	v_and_b32_e32 v71, 0xffff0000, v47
	v_mul_f32_e32 v37, 0x3d372713, v71
	v_fma_f32 v37, v37, v71, 1.0
	v_add_f32_e32 v36, 1.0, v36
	v_rcp_f32_e32 v77, v36
	v_mul_f32_e32 v36, 0x3fcc422a, v71
	v_mul_f32_e32 v36, v36, v37
	v_mul_f32_e32 v36, 0xbfb8aa3b, v36
	v_exp_f32_e32 v36, v36
	v_mul_f32_e32 v37, 0x3d372713, v70
	v_fma_f32 v37, v37, v70, 1.0
	v_fma_f32 v46, v75, v73, 0
	v_add_f32_e32 v36, 1.0, v36
	v_rcp_f32_e32 v78, v36
	v_mul_f32_e32 v36, 0x3fcc422a, v70
	v_mul_f32_e32 v36, v36, v37
	v_mul_f32_e32 v36, 0xbfb8aa3b, v36
	v_exp_f32_e32 v36, v36
	v_mul_f32_e32 v37, 0x3d372713, v69
	v_fma_f32 v37, v37, v69, 1.0
	v_fmac_f32_e32 v46, v76, v74
	v_add_f32_e32 v36, 1.0, v36
	v_rcp_f32_e32 v79, v36
	v_mul_f32_e32 v36, 0x3fcc422a, v69
	v_mul_f32_e32 v36, v36, v37
	v_mul_f32_e32 v36, 0xbfb8aa3b, v36
	v_exp_f32_e32 v36, v36
	v_mul_f32_e32 v37, 0x3d372713, v68
	v_fma_f32 v37, v37, v68, 1.0
	v_fmac_f32_e32 v46, v77, v72
	v_add_f32_e32 v36, 1.0, v36
	v_rcp_f32_e32 v80, v36
	v_mul_f32_e32 v36, 0x3fcc422a, v68
	v_mul_f32_e32 v36, v36, v37
	v_mul_f32_e32 v36, 0xbfb8aa3b, v36
	v_exp_f32_e32 v36, v36
	v_mul_f32_e32 v37, 0x3d372713, v67
	v_fma_f32 v37, v37, v67, 1.0
	v_fmac_f32_e32 v46, v78, v71
	v_add_f32_e32 v36, 1.0, v36
	v_rcp_f32_e32 v81, v36
	v_mul_f32_e32 v36, 0x3fcc422a, v67
	v_mul_f32_e32 v36, v36, v37
	v_mul_f32_e32 v36, 0xbfb8aa3b, v36
	v_exp_f32_e32 v36, v36
	v_mul_f32_e32 v37, 0x3d372713, v66
	v_fma_f32 v37, v37, v66, 1.0
	v_fmac_f32_e32 v46, v79, v70
	v_add_f32_e32 v36, 1.0, v36
	v_rcp_f32_e32 v82, v36
	v_mul_f32_e32 v36, 0x3fcc422a, v66
	v_mul_f32_e32 v36, v36, v37
	v_mul_f32_e32 v36, 0xbfb8aa3b, v36
	v_exp_f32_e32 v36, v36
	v_mul_f32_e32 v37, 0x3d372713, v65
	v_fma_f32 v37, v37, v65, 1.0
	v_fmac_f32_e32 v46, v80, v69
	v_add_f32_e32 v36, 1.0, v36
	v_rcp_f32_e32 v84, v36
	v_mul_f32_e32 v36, 0x3fcc422a, v65
	v_mul_f32_e32 v36, v36, v37
	v_mul_f32_e32 v36, 0xbfb8aa3b, v36
	v_exp_f32_e32 v36, v36
	v_mul_f32_e32 v37, 0x3d372713, v64
	v_fma_f32 v37, v37, v64, 1.0
	v_fmac_f32_e32 v46, v81, v68
	v_add_f32_e32 v36, 1.0, v36
	v_rcp_f32_e32 v85, v36
	v_mul_f32_e32 v36, 0x3fcc422a, v64
	v_mul_f32_e32 v36, v36, v37
	v_mul_f32_e32 v36, 0xbfb8aa3b, v36
	v_exp_f32_e32 v36, v36
	v_mul_f32_e32 v37, 0x3d372713, v63
	v_fma_f32 v37, v37, v63, 1.0
	v_fmac_f32_e32 v46, v82, v67
	v_add_f32_e32 v36, 1.0, v36
	v_rcp_f32_e32 v86, v36
	v_mul_f32_e32 v36, 0x3fcc422a, v63
	v_mul_f32_e32 v36, v36, v37
	v_mul_f32_e32 v36, 0xbfb8aa3b, v36
	v_exp_f32_e32 v36, v36
	v_mul_f32_e32 v37, 0x3d372713, v62
	v_fma_f32 v37, v37, v62, 1.0
	v_fmac_f32_e32 v46, v84, v66
	v_add_f32_e32 v36, 1.0, v36
	v_rcp_f32_e32 v87, v36
	v_mul_f32_e32 v36, 0x3fcc422a, v62
	v_mul_f32_e32 v36, v36, v37
	v_mul_f32_e32 v36, 0xbfb8aa3b, v36
	v_exp_f32_e32 v36, v36
	v_mul_f32_e32 v37, 0x3d372713, v61
	v_fma_f32 v37, v37, v61, 1.0
	v_fmac_f32_e32 v46, v85, v65
	v_add_f32_e32 v36, 1.0, v36
	v_rcp_f32_e32 v88, v36
	v_mul_f32_e32 v36, 0x3fcc422a, v61
	v_mul_f32_e32 v36, v36, v37
	v_mul_f32_e32 v36, 0xbfb8aa3b, v36
	v_exp_f32_e32 v36, v36
	v_mul_f32_e32 v37, 0x3d372713, v60
	v_fma_f32 v37, v37, v60, 1.0
	v_fmac_f32_e32 v46, v86, v64
	v_add_f32_e32 v36, 1.0, v36
	v_rcp_f32_e32 v89, v36
	v_mul_f32_e32 v36, 0x3fcc422a, v60
	v_mul_f32_e32 v36, v36, v37
	v_mul_f32_e32 v36, 0xbfb8aa3b, v36
	v_exp_f32_e32 v36, v36
	v_mul_f32_e32 v37, 0x3d372713, v59
	v_fma_f32 v37, v37, v59, 1.0
	v_mul_f32_e32 v47, 0x3d372713, v42
	v_add_f32_e32 v36, 1.0, v36
	v_rcp_f32_e32 v90, v36
	v_mul_f32_e32 v36, 0x3fcc422a, v59
	v_mul_f32_e32 v36, v36, v37
; __device__ __forceinline__ float gelu_f(float x) { const float y2 = 1.5957691216057308f * x * (1.0f + 0.044715f * x * x); return x * sigmoid_f(y2); }
; #define LAS __attribute__((address_space(3)))
; __device__ __forceinline__ void p2_block(LAS unsigned char* lds, const bf16_t* __restrict__ PROJ, bf16_t* __restrict__ ATT, bf16_t* __restrict__ SGU, const float* __restrict__ qn, const float* __restrict__ kn, ...
;     ...
;         for (int c4 = 0; c4 < 4; ++c4) { u32x4 t = vv[c4]; if (s < 0) t = (u32x4){0u, 0u, 0u, 0u};
;             LAS unsigned char* vd = VT + (32 * h + 8 * c4) * VT_STRIDE + kk * 2;
;             *(LAS unsigned short*)(vd + 0 * VT_STRIDE) = (unsigned short)(t.x & 0xffffu); *(LAS unsigned short*)(vd + 1 * VT_STRIDE) = (unsigned short)(t.x >> 16);
;             *(LAS unsigned short*)(vd + 2 * VT_STRIDE) = (unsigned short)(t.y & 0xffffu); *(LAS unsigned short*)(vd + 3 * VT_STRIDE) = (unsigned short)(t.y >> 16);
;             *(LAS unsigned short*)(vd + 4 * VT_STRIDE) = (unsigned short)(t.z & 0xffffu); *(LAS unsigned short*)(vd + 5 * VT_STRIDE) = (unsigned short)(t.z >> 16);
;             *(LAS unsigned short*)(vd + 6 * VT_STRIDE) = (unsigned short)(t.w & 0xffffu); *(LAS unsigned short*)(vd + 7 * VT_STRIDE) = (unsigned short)(t.w >> 16); }
;     ...
;         for (int j = 0; j < 32; ++j) { v[j] = gelu_f(v[j]); sm += v[j]; }
	v_mul_f32_e32 v36, 0xbfb8aa3b, v36
	v_exp_f32_e32 v36, v36
	v_mul_f32_e32 v37, 0x3d372713, v58
	v_fma_f32 v37, v37, v58, 1.0
	v_fmac_f32_e32 v46, v87, v63
	v_add_f32_e32 v36, 1.0, v36
	v_rcp_f32_e32 v91, v36
	v_mul_f32_e32 v36, 0x3fcc422a, v58
	v_mul_f32_e32 v36, v36, v37
	v_mul_f32_e32 v36, 0xbfb8aa3b, v36
	v_exp_f32_e32 v36, v36
	v_mul_f32_e32 v37, 0x3d372713, v57
	v_fma_f32 v37, v37, v57, 1.0
	v_fma_f32 v47, v47, v42, 1.0
	v_add_f32_e32 v36, 1.0, v36
	v_rcp_f32_e32 v98, v36
	v_mul_f32_e32 v36, 0x3fcc422a, v57
	v_mul_f32_e32 v36, v36, v37
	v_mul_f32_e32 v36, 0xbfb8aa3b, v36
	v_exp_f32_e32 v36, v36
	v_mul_f32_e32 v37, 0x3d372713, v56
	v_fma_f32 v37, v37, v56, 1.0
	v_fmac_f32_e32 v46, v88, v62
	v_add_f32_e32 v36, 1.0, v36
	v_rcp_f32_e32 v99, v36
	v_mul_f32_e32 v36, 0x3fcc422a, v56
	v_mul_f32_e32 v36, v36, v37
	v_mul_f32_e32 v36, 0xbfb8aa3b, v36
	v_exp_f32_e32 v36, v36
	v_mul_f32_e32 v37, 0x3d372713, v55
	v_fma_f32 v37, v37, v55, 1.0
	v_fmac_f32_e32 v46, v89, v61
	v_add_f32_e32 v36, 1.0, v36
	v_rcp_f32_e32 v100, v36
	v_mul_f32_e32 v36, 0x3fcc422a, v55
	v_mul_f32_e32 v36, v36, v37
	v_mul_f32_e32 v36, 0xbfb8aa3b, v36
	v_exp_f32_e32 v36, v36
	v_mul_f32_e32 v37, 0x3d372713, v49
	v_fma_f32 v37, v37, v49, 1.0
	v_fmac_f32_e32 v46, v90, v60
	v_add_f32_e32 v36, 1.0, v36
	v_rcp_f32_e32 v101, v36
	v_mul_f32_e32 v36, 0x3fcc422a, v49
	v_mul_f32_e32 v36, v36, v37
	v_mul_f32_e32 v36, 0xbfb8aa3b, v36
	v_exp_f32_e32 v36, v36
	v_mul_f32_e32 v37, 0x3d372713, v48
	v_fma_f32 v37, v37, v48, 1.0
	v_fmac_f32_e32 v46, v91, v59
	v_add_f32_e32 v36, 1.0, v36
	v_rcp_f32_e32 v102, v36
	v_mul_f32_e32 v36, 0x3fcc422a, v48
	v_mul_f32_e32 v36, v36, v37
	v_mul_f32_e32 v36, 0xbfb8aa3b, v36
	v_exp_f32_e32 v36, v36
	v_mul_f32_e32 v37, 0x3d372713, v45
	v_fma_f32 v37, v37, v45, 1.0
	v_fmac_f32_e32 v46, v98, v58
	v_add_f32_e32 v36, 1.0, v36
	v_rcp_f32_e32 v103, v36
	v_mul_f32_e32 v36, 0x3fcc422a, v45
	v_mul_f32_e32 v36, v36, v37
	v_mul_f32_e32 v36, 0xbfb8aa3b, v36
	v_exp_f32_e32 v36, v36
	v_mul_f32_e32 v37, 0x3d372713, v44
	v_fma_f32 v37, v37, v44, 1.0
	v_fmac_f32_e32 v46, v99, v57
	v_add_f32_e32 v36, 1.0, v36
	v_rcp_f32_e32 v104, v36
	v_mul_f32_e32 v36, 0x3fcc422a, v44
	v_mul_f32_e32 v36, v36, v37
	v_mul_f32_e32 v36, 0xbfb8aa3b, v36
	v_exp_f32_e32 v36, v36
	v_mul_f32_e32 v37, 0x3d372713, v43
	v_fma_f32 v37, v37, v43, 1.0
	v_fmac_f32_e32 v46, v100, v56
	v_add_f32_e32 v36, 1.0, v36
	v_rcp_f32_e32 v105, v36
	v_mul_f32_e32 v36, 0x3fcc422a, v43
	v_mul_f32_e32 v36, v36, v37
	v_mul_f32_e32 v36, 0xbfb8aa3b, v36
	v_exp_f32_e32 v36, v36
	v_fmac_f32_e32 v46, v101, v55
	v_fmac_f32_e32 v46, v102, v49
	v_fmac_f32_e32 v46, v103, v48
	v_add_f32_e32 v36, 1.0, v36
	v_rcp_f32_e32 v37, v36
	v_mul_f32_e32 v36, 0x3fcc422a, v42
	v_mul_f32_e32 v36, v36, v47
	v_mul_f32_e32 v36, 0xbfb8aa3b, v36
	v_exp_f32_e32 v36, v36
	v_fmac_f32_e32 v46, v104, v45
	v_fmac_f32_e32 v46, v105, v44
	v_mul_f32_e32 v47, 0x3d372713, v41
	v_add_f32_e32 v36, 1.0, v36
	v_rcp_f32_e32 v36, v36
	v_fma_f32 v47, v47, v41, 1.0
	v_mul_f32_e32 v94, 0x3d372713, v38
	v_fma_f32 v94, v94, v38, 1.0
	v_pk_mul_f32 v[92:93], v[36:37], v[42:43]
	v_mul_f32_e32 v96, 0x3d372713, v34
	v_add_f32_e32 v46, v93, v46
	v_add_f32_e32 v83, v92, v46
	v_mul_f32_e32 v46, 0x3fcc422a, v41
	v_mul_f32_e32 v46, v46, v47
	v_mul_f32_e32 v46, 0xbfb8aa3b, v46
	v_exp_f32_e32 v46, v46
	v_mul_f32_e32 v92, 0x3d372713, v40
	v_fma_f32 v92, v92, v40, 1.0
	v_fma_f32 v96, v96, v34, 1.0
	v_add_f32_e32 v46, 1.0, v46
	v_rcp_f32_e32 v47, v46
	v_mul_f32_e32 v46, 0x3fcc422a, v40
	v_mul_f32_e32 v46, v46, v92
	v_mul_f32_e32 v46, 0xbfb8aa3b, v46
	v_exp_f32_e32 v46, v46
	v_and_b32_e32 v0, -2, v160
	v_mul_u32_u24_e32 v50, 0x4200, v166
	s_waitcnt vmcnt(16)
	v_cndmask_b32_e64 v18, v18, 0, vcc
	v_add_f32_e32 v46, 1.0, v46
	v_rcp_f32_e32 v46, v46
	v_add3_u32 v0, 0, v0, v50
	v_cndmask_b32_e64 v14, v14, 0, vcc
	v_cndmask_b32_e64 v10, v10, 0, vcc
	v_pk_mul_f32 v[92:93], v[46:47], v[40:41]
	v_cndmask_b32_e64 v6, v6, 0, vcc
	v_add_f32_e32 v83, v93, v83
	v_mul_f32_e32 v93, 0x3d372713, v39
	v_add_f32_e32 v83, v92, v83
	v_mul_f32_e32 v92, 0x3fcc422a, v39
	v_fma_f32 v93, v93, v39, 1.0
	v_mul_f32_e32 v92, v92, v93
	v_mul_f32_e32 v92, 0xbfb8aa3b, v92
	v_exp_f32_e32 v92, v92
	v_cndmask_b32_e64 v21, v21, 0, vcc
	v_cndmask_b32_e64 v20, v20, 0, vcc
	v_cndmask_b32_e64 v19, v19, 0, vcc
	v_add_f32_e32 v92, 1.0, v92
	v_rcp_f32_e32 v93, v92
	v_mul_f32_e32 v92, 0x3fcc422a, v38
	v_mul_f32_e32 v92, v92, v94
	v_mul_f32_e32 v92, 0xbfb8aa3b, v92
	v_exp_f32_e32 v92, v92
	ds_write_b16 v0, v18 offset:36864
	ds_write_b16_d16_hi v0, v18 offset:37392
	ds_write_b16 v0, v19 offset:37920
	ds_write_b16_d16_hi v0, v19 offset:38448
	ds_write_b16 v0, v20 offset:38976
	ds_write_b16_d16_hi v0, v20 offset:39504
	ds_write_b16 v0, v21 offset:40032
	ds_write_b16_d16_hi v0, v21 offset:40560
	v_cndmask_b32_e64 v17, v17, 0, vcc
	v_cndmask_b32_e64 v16, v16, 0, vcc
	v_add_f32_e32 v92, 1.0, v92
	v_rcp_f32_e32 v92, v92
	v_cndmask_b32_e64 v15, v15, 0, vcc
	ds_write_b16 v0, v14 offset:41088
	ds_write_b16_d16_hi v0, v14 offset:41616
	ds_write_b16 v0, v15 offset:42144
	ds_write_b16_d16_hi v0, v15 offset:42672
	ds_write_b16 v0, v16 offset:43200
	ds_write_b16_d16_hi v0, v16 offset:43728
	ds_write_b16 v0, v17 offset:44256
	ds_write_b16_d16_hi v0, v17 offset:44784
	v_cndmask_b32_e64 v13, v13, 0, vcc
	v_pk_mul_f32 v[94:95], v[92:93], v[38:39]
	v_cndmask_b32_e64 v12, v12, 0, vcc
	v_add_f32_e32 v83, v95, v83
	v_mul_f32_e32 v95, 0x3d372713, v35
	v_add_f32_e32 v83, v94, v83
	v_mul_f32_e32 v94, 0x3fcc422a, v35
	v_fma_f32 v95, v95, v35, 1.0
	v_mul_f32_e32 v94, v94, v95
	v_mul_f32_e32 v94, 0xbfb8aa3b, v94
	v_exp_f32_e32 v94, v94
	v_cndmask_b32_e64 v11, v11, 0, vcc
; __device__ __forceinline__ float gelu_f(float x) { const float y2 = 1.5957691216057308f * x * (1.0f + 0.044715f * x * x); return x * sigmoid_f(y2); }
; #define LAS __attribute__((address_space(3)))
; __device__ __forceinline__ void unpack8(const u32x4 w, float* f) { f[0] = bf_lo(w.x); f[1] = bf_hi(w.x); f[2] = bf_lo(w.y); f[3] = bf_hi(w.y); f[4] = bf_lo(w.z); f[5] = bf_hi(w.z); f[6] = bf_lo(w.w); f[7] = bf_hi(w.w); }
; __device__ __forceinline__ void p2_block(LAS unsigned char* lds, const bf16_t* __restrict__ PROJ, bf16_t* __restrict__ ATT, bf16_t* __restrict__ SGU, const float* __restrict__ qn, const float* __restrict__ kn, ...
;     ...
;         for (int c4 = 0; c4 < 4; ++c4) { u32x4 t = vv[c4]; if (s < 0) t = (u32x4){0u, 0u, 0u, 0u};
;             LAS unsigned char* vd = VT + (32 * h + 8 * c4) * VT_STRIDE + kk * 2;
;             *(LAS unsigned short*)(vd + 0 * VT_STRIDE) = (unsigned short)(t.x & 0xffffu); *(LAS unsigned short*)(vd + 1 * VT_STRIDE) = (unsigned short)(t.x >> 16);
;             *(LAS unsigned short*)(vd + 2 * VT_STRIDE) = (unsigned short)(t.y & 0xffffu); *(LAS unsigned short*)(vd + 3 * VT_STRIDE) = (unsigned short)(t.y >> 16);
;             *(LAS unsigned short*)(vd + 4 * VT_STRIDE) = (unsigned short)(t.z & 0xffffu); *(LAS unsigned short*)(vd + 5 * VT_STRIDE) = (unsigned short)(t.z >> 16);
;             *(LAS unsigned short*)(vd + 6 * VT_STRIDE) = (unsigned short)(t.w & 0xffffu); *(LAS unsigned short*)(vd + 7 * VT_STRIDE) = (unsigned short)(t.w >> 16); }
;     }
; #pragma unroll
;     for (int gi = 0; gi < 2; ++gi) {
;         const int gg = 2 * kvh + gi;
;         if (gi == 0) {
; #pragma unroll
;             for (int c4 = 0; c4 < 4; ++c4) sv[1][c4] = *(const u32x4*)(svsrc + 128 + 8 * c4); }
;         float v[32];
; #pragma unroll
;         for (int c4 = 0; c4 < 4; ++c4) unpack8(sv[gi][c4], v + 8 * c4);
;         float sm = 0.f;
; #pragma unroll
;         for (int j = 0; j < 32; ++j) { v[j] = gelu_f(v[j]); sm += v[j]; }
;         sm += __shfl_xor(sm, 1); sm += __shfl_xor(sm, 2);
;         const float mu = sm * (1.0f / 128.0f); float q = 0.f;
; #pragma unroll
;         for (int j = 0; j < 32; ++j) { v[j] -= mu; q += v[j] * v[j]; }
;         q += __shfl_xor(q, 1); q += __shfl_xor(q, 2);
;         const float rstd = rsqrtf(q * (1.0f / 128.0f) + pg8::EPS);
	ds_write_b16 v0, v10 offset:45312
	ds_write_b16_d16_hi v0, v10 offset:45840
	ds_write_b16 v0, v11 offset:46368
	ds_write_b16_d16_hi v0, v11 offset:46896
	ds_write_b16 v0, v12 offset:47424
	ds_write_b16_d16_hi v0, v12 offset:47952
	ds_write_b16 v0, v13 offset:48480
	ds_write_b16_d16_hi v0, v13 offset:49008
	v_cndmask_b32_e64 v9, v9, 0, vcc
	v_add_f32_e32 v94, 1.0, v94
	v_rcp_f32_e32 v95, v94
	v_mul_f32_e32 v94, 0x3fcc422a, v34
	v_mul_f32_e32 v94, v94, v96
	v_mul_f32_e32 v94, 0xbfb8aa3b, v94
	v_exp_f32_e32 v94, v94
	v_cndmask_b32_e64 v8, v8, 0, vcc
	v_cndmask_b32_e64 v7, v7, 0, vcc
	ds_write_b16 v0, v6 offset:49536
	ds_write_b16_d16_hi v0, v6 offset:50064
	ds_write_b16 v0, v7 offset:50592
	ds_write_b16_d16_hi v0, v7 offset:51120
	ds_write_b16 v0, v8 offset:51648
	ds_write_b16_d16_hi v0, v8 offset:52176
	ds_write_b16 v0, v9 offset:52704
	ds_write_b16_d16_hi v0, v9 offset:53232
	v_add_f32_e32 v94, 1.0, v94
	v_rcp_f32_e32 v94, v94
	v_xor_b32_e32 v0, 2, v211
	v_cmp_lt_i32_e32 vcc, v0, v133
	v_lshlrev_b32_e32 v6, 1, v136
	v_pk_mul_f32 v[96:97], v[94:95], v[34:35]
	v_cndmask_b32_e32 v0, v211, v0, vcc
	v_add_f32_e32 v83, v97, v83
	v_add_f32_e32 v83, v96, v83
	s_nop 1
	v_mov_b32_dpp v96, v83 quad_perm:[1,0,3,2] row_mask:0xf bank_mask:0xf
	v_lshlrev_b32_e32 v54, 2, v0
	v_lshlrev_b32_e32 v0, 2, v165
	v_lshl_add_u64 v[50:51], s[36:37], 0, v[0:1]
	v_lshl_add_u64 v[52:53], s[18:19], 0, v[0:1]
	s_waitcnt lgkmcnt(0)
	v_add_f32_e32 v83, v83, v96
	s_nop 1
	v_mov_b32_dpp v96, v83 quad_perm:[2,3,0,1] row_mask:0xf bank_mask:0xf
	v_mul_u32_u24_e32 v0, 0x110, v165
	v_add3_u32 v0, 0, v0, v6
	global_load_dwordx4 v[6:9], v[138:139], off offset:304
	global_load_dwordx4 v[10:13], v[138:139], off offset:288
	global_load_dwordx4 v[14:17], v[138:139], off offset:272
	global_load_dwordx4 v[18:21], v[138:139], off offset:256
	s_ashr_i32 s43, s42, 31
	s_waitcnt lgkmcnt(0)
	v_add_f32_e32 v83, v83, v96
	v_mul_f32_e32 v96, 0x3c000000, v83
	v_fma_f32 v83, v76, v74, -v96
	v_fma_f32 v97, v75, v73, -v96
	v_mul_f32_e32 v106, v83, v83
	v_fmac_f32_e32 v106, v97, v97
	v_fma_f32 v77, v77, v72, -v96
	v_fmac_f32_e32 v106, v77, v77
	v_fma_f32 v76, v78, v71, -v96
	v_fmac_f32_e32 v106, v76, v76
	v_fma_f32 v75, v79, v70, -v96
	v_fmac_f32_e32 v106, v75, v75
	v_fma_f32 v74, v80, v69, -v96
	v_fmac_f32_e32 v106, v74, v74
	v_fma_f32 v73, v81, v68, -v96
	v_fmac_f32_e32 v106, v73, v73
	v_fma_f32 v72, v82, v67, -v96
	v_fmac_f32_e32 v106, v72, v72
	v_fma_f32 v71, v84, v66, -v96
	v_fmac_f32_e32 v106, v71, v71
	v_fma_f32 v70, v85, v65, -v96
	v_fmac_f32_e32 v106, v70, v70
	v_fma_f32 v69, v86, v64, -v96
	v_fmac_f32_e32 v106, v69, v69
	v_fma_f32 v68, v87, v63, -v96
	v_fmac_f32_e32 v106, v68, v68
	v_fma_f32 v67, v88, v62, -v96
	v_fmac_f32_e32 v106, v67, v67
	v_fma_f32 v66, v89, v61, -v96
	v_fmac_f32_e32 v106, v66, v66
	v_fma_f32 v65, v90, v60, -v96
	v_fmac_f32_e32 v106, v65, v65
	v_fma_f32 v64, v91, v59, -v96
	v_fmac_f32_e32 v106, v64, v64
	v_fma_f32 v63, v98, v58, -v96
	v_fmac_f32_e32 v106, v63, v63
	v_fma_f32 v62, v99, v57, -v96
	v_fmac_f32_e32 v106, v62, v62
	v_fma_f32 v61, v100, v56, -v96
	v_fmac_f32_e32 v106, v61, v61
	v_fma_f32 v60, v101, v55, -v96
	v_fmac_f32_e32 v106, v60, v60
	v_fma_f32 v59, v102, v49, -v96
	v_fmac_f32_e32 v106, v59, v59
	v_fma_f32 v58, v103, v48, -v96
	v_fmac_f32_e32 v106, v58, v58
	v_fma_f32 v57, v104, v45, -v96
	v_fmac_f32_e32 v106, v57, v57
	v_fma_f32 v56, v105, v44, -v96
	v_pk_fma_f32 v[44:45], v[36:37], v[42:43], v[96:97] op_sel_hi:[1,1,0] neg_lo:[0,0,1] neg_hi:[0,0,1]
	v_fmac_f32_e32 v106, v56, v56
	v_pk_mul_f32 v[36:37], v[44:45], v[44:45]
	v_pk_fma_f32 v[42:43], v[46:47], v[40:41], v[96:97] op_sel_hi:[1,1,0] neg_lo:[0,0,1] neg_hi:[0,0,1]
	v_add_f32_e32 v37, v37, v106
	v_add_f32_e32 v48, v36, v37
	v_pk_mul_f32 v[36:37], v[42:43], v[42:43]
	v_pk_fma_f32 v[40:41], v[92:93], v[38:39], v[96:97] op_sel_hi:[1,1,0] neg_lo:[0,0,1] neg_hi:[0,0,1]
	v_add_f32_e32 v37, v37, v48
	v_add_f32_e32 v46, v36, v37
	v_pk_mul_f32 v[36:37], v[40:41], v[40:41]
	v_pk_fma_f32 v[38:39], v[94:95], v[34:35], v[96:97] op_sel_hi:[1,1,0] neg_lo:[0,0,1] neg_hi:[0,0,1]
	v_add_f32_e32 v37, v37, v46
	v_add_f32_e32 v36, v36, v37
	v_pk_mul_f32 v[34:35], v[38:39], v[38:39]
	v_lshlrev_b32_e32 v105, 16, v3
	v_add_f32_e32 v35, v35, v36
	v_add_f32_e32 v34, v34, v35
	s_nop 1
	v_mov_b32_dpp v35, v34 quad_perm:[1,0,3,2] row_mask:0xf bank_mask:0xf
	v_lshl_add_u64 v[36:37], v[52:53], 0, s[4:5]
	v_and_b32_e32 v109, 0xffff0000, v3
	v_lshlrev_b32_e32 v113, 16, v2
	v_lshlrev_b32_e32 v112, 16, v30
	s_waitcnt lgkmcnt(0)
	v_add_f32_e32 v34, v34, v35
	s_nop 1
	v_mov_b32_dpp v35, v34 quad_perm:[2,3,0,1] row_mask:0xf bank_mask:0xf
	v_and_b32_e32 v3, 0xffff0000, v2
	v_and_b32_e32 v2, 0xffff0000, v30
	v_and_b32_e32 v96, 0xffff0000, v33
	s_waitcnt vmcnt(1)
	v_lshlrev_b32_e32 v53, 16, v14
	s_waitcnt lgkmcnt(0)
	v_add_f32_e32 v34, v34, v35
	v_fmamk_f32 v34, v34, 0x3c000000, v209
	v_cmp_gt_f32_e32 vcc, s82, v34
	v_mul_f32_e32 v35, 0x4b800000, v34
	v_and_b32_e32 v52, 0xffff0000, v14
	v_cndmask_b32_e32 v34, v34, v35, vcc
	v_rsq_f32_e32 v34, v34
	v_and_b32_e32 v14, 0xffff0000, v6
	v_lshlrev_b32_e32 v104, 16, v31
	v_and_b32_e32 v108, 0xffff0000, v31
	v_mul_f32_e32 v35, 0x45800000, v34
	v_cndmask_b32_e32 v55, v34, v35, vcc
	v_lshl_add_u64 v[34:35], v[50:51], 0, s[4:5]
	v_mov_b64_e32 v[46:47], v[144:145]
	v_mov_b64_e32 v[48:49], v[218:219]
	v_mul_f32_e32 v51, v97, v55
	v_add_u32_e32 v50, 0x11800, v0
	v_mul_f32_e32 v45, v45, v55
	v_mul_f32_e32 v44, v44, v55
	v_mul_f32_e32 v43, v43, v55
	v_mul_f32_e32 v42, v42, v55
	v_mul_f32_e32 v41, v41, v55
	v_mul_f32_e32 v40, v40, v55
	v_mul_f32_e32 v39, v39, v55
	v_mul_f32_e32 v38, v38, v55
	v_mov_b32_e32 v116, v112
	v_mov_b32_e32 v117, v2
	v_and_b32_e32 v97, 0xffff0000, v5
	v_mov_b32_e32 v110, v108
	v_mov_b32_e32 v111, v104
	v_mov_b32_e32 v30, v113
	v_mov_b32_e32 v31, v3
	v_pk_mul_f32 v[116:117], v[116:117], v[116:117]
	v_lshlrev_b32_e32 v101, 16, v4
	v_lshlrev_b32_e32 v100, 16, v32
	v_pk_mul_f32 v[110:111], v[110:111], v[110:111]
	v_pk_fma_f32 v[30:31], v[30:31], v[30:31], v[116:117]
	v_lshlrev_b32_e32 v130, 3, v162
	v_mov_b32_e32 v131, v1
	s_mov_b32 s4, s5
	s_mov_b32 s52, 0xf149f2ca
	s_waitcnt vmcnt(0)
; __device__ __forceinline__ unsigned cvt_pk_bf16(float lo, float hi) { unsigned r; asm volatile("v_cvt_pk_bf16_f32 %0, %1, %2" : "=v"(r) : "v"(lo), "v"(hi)); return r; }
; __device__ __forceinline__ float gelu_f(float x) { const float y2 = 1.5957691216057308f * x * (1.0f + 0.044715f * x * x); return x * sigmoid_f(y2); }
; #define LAS __attribute__((address_space(3)))
; __device__ __forceinline__ void unpack8(const u32x4 w, float* f) { f[0] = bf_lo(w.x); f[1] = bf_hi(w.x); f[2] = bf_lo(w.y); f[3] = bf_hi(w.y); f[4] = bf_lo(w.z); f[5] = bf_hi(w.z); f[6] = bf_lo(w.w); f[7] = bf_hi(w.w); }
; __device__ __forceinline__ void p2_block(LAS unsigned char* lds, const bf16_t* __restrict__ PROJ, bf16_t* __restrict__ ATT, bf16_t* __restrict__ SGU, const float* __restrict__ qn, const float* __restrict__ kn, ...
;     ...
;         float v[32];
; #pragma unroll
;         for (int c4 = 0; c4 < 4; ++c4) unpack8(sv[gi][c4], v + 8 * c4);
;         float sm = 0.f;
; #pragma unroll
;         for (int j = 0; j < 32; ++j) { v[j] = gelu_f(v[j]); sm += v[j]; }
;     ...
;         const float* gp = lng + gg * 128 + 32 * q4; const float* bp = lnb + gg * 128 + 32 * q4;
;         LAS unsigned char* dst = lds + (gi ? VN_OFF1 : VN_OFF0) + (32 * q4) * VN_STRIDE + sp_ * 2;
; #pragma unroll
;         for (int j = 0; j < 32; j += 2) { const unsigned pk = cvt_pk_bf16(v[j] * rstd * gp[j] + bp[j], v[j + 1] * rstd * gp[j + 1] + bp[j + 1]);
;             *(LAS unsigned short*)(dst + j * VN_STRIDE) = (unsigned short)(pk & 0xffffu); *(LAS unsigned short*)(dst + (j + 1) * VN_STRIDE) = (unsigned short)(pk >> 16); }
	v_fma_f32 v46, v46, v51, v48
	v_mul_f32_e32 v48, v83, v55
	v_fmac_f32_e32 v49, v47, v48
	v_add_u32_e32 v47, 0x11910, v0
	v_cvt_pk_bf16_f32 v46, v46, v49
	ds_write_b16 v50, v46
	ds_write_b16_d16_hi v47, v46
	v_mov_b64_e32 v[46:47], v[146:147]
	v_mov_b64_e32 v[48:49], v[220:221]
	v_mul_f32_e32 v50, v77, v55
	v_lshlrev_b32_e32 v51, 16, v15
	s_waitcnt vmcnt(0)
	v_fma_f32 v46, v46, v50, v48
	v_mul_f32_e32 v48, v76, v55
	v_fmac_f32_e32 v49, v47, v48
	v_add_u32_e32 v47, 0x11a20, v0
	v_cvt_pk_bf16_f32 v46, v46, v49
	ds_write_b16 v47, v46
	v_add_u32_e32 v47, 0x11b30, v0
	ds_write_b16_d16_hi v47, v46
	v_mov_b64_e32 v[46:47], v[148:149]
	v_mov_b64_e32 v[48:49], v[222:223]
	v_mul_f32_e32 v50, v75, v55
	s_waitcnt vmcnt(0)
	v_fma_f32 v46, v46, v50, v48
	v_mul_f32_e32 v48, v74, v55
	v_fmac_f32_e32 v49, v47, v48
	v_add_u32_e32 v47, 0x11c40, v0
	v_cvt_pk_bf16_f32 v46, v46, v49
	ds_write_b16 v47, v46
	v_add_u32_e32 v47, 0x11d50, v0
	ds_write_b16_d16_hi v47, v46
	v_mov_b64_e32 v[46:47], v[150:151]
	v_mov_b64_e32 v[48:49], v[224:225]
	v_mul_f32_e32 v50, v73, v55
	s_waitcnt vmcnt(0)
	v_fma_f32 v46, v46, v50, v48
	v_mul_f32_e32 v48, v72, v55
	v_fmac_f32_e32 v49, v47, v48
	v_add_u32_e32 v47, 0x11e60, v0
	v_cvt_pk_bf16_f32 v46, v46, v49
	ds_write_b16 v47, v46
	v_add_u32_e32 v47, 0x11f70, v0
	ds_write_b16_d16_hi v47, v46
	v_mov_b64_e32 v[46:47], v[152:153]
	v_mov_b64_e32 v[48:49], v[226:227]
	v_mul_f32_e32 v50, v71, v55
	s_waitcnt vmcnt(0)
	v_fma_f32 v46, v46, v50, v48
	v_mul_f32_e32 v48, v70, v55
	v_fmac_f32_e32 v49, v47, v48
	v_add_u32_e32 v47, 0x12080, v0
	v_cvt_pk_bf16_f32 v46, v46, v49
	ds_write_b16 v47, v46
	v_add_u32_e32 v47, 0x12190, v0
	ds_write_b16_d16_hi v47, v46
	v_mov_b64_e32 v[46:47], v[154:155]
	v_mov_b64_e32 v[48:49], v[228:229]
	v_mul_f32_e32 v50, v69, v55
	s_waitcnt vmcnt(0)
	v_fma_f32 v46, v46, v50, v48
	v_mul_f32_e32 v48, v68, v55
	v_fmac_f32_e32 v49, v47, v48
	v_add_u32_e32 v47, 0x122a0, v0
	v_cvt_pk_bf16_f32 v46, v46, v49
	ds_write_b16 v47, v46
	v_add_u32_e32 v47, 0x123b0, v0
	ds_write_b16_d16_hi v47, v46
	v_mov_b64_e32 v[46:47], v[156:157]
	v_mov_b64_e32 v[48:49], v[230:231]
	v_mul_f32_e32 v50, v67, v55
	s_waitcnt vmcnt(0)
	v_fma_f32 v46, v46, v50, v48
	v_mul_f32_e32 v48, v66, v55
	v_fmac_f32_e32 v49, v48, v47
	v_add_u32_e32 v47, 0x124c0, v0
	v_cvt_pk_bf16_f32 v46, v46, v49
	ds_write_b16 v47, v46
	v_add_u32_e32 v47, 0x125d0, v0
	ds_write_b16_d16_hi v47, v46
	v_mov_b64_e32 v[46:47], v[158:159]
	v_mov_b64_e32 v[48:49], v[232:233]
	v_mul_f32_e32 v50, v65, v55
	s_waitcnt vmcnt(0)
	v_fma_f32 v46, v50, v46, v48
	v_mul_f32_e32 v48, v64, v55
	v_fmac_f32_e32 v49, v48, v47
	v_add_u32_e32 v47, 0x126e0, v0
	v_cvt_pk_bf16_f32 v46, v46, v49
	ds_write_b16 v47, v46
	v_add_u32_e32 v47, 0x127f0, v0
	ds_write_b16_d16_hi v47, v46
	v_mov_b64_e32 v[46:47], v[184:185]
	v_mov_b64_e32 v[48:49], v[234:235]
	v_mul_f32_e32 v50, v63, v55
	s_waitcnt vmcnt(0)
	v_fma_f32 v46, v50, v46, v48
	v_mul_f32_e32 v48, v62, v55
	v_fmac_f32_e32 v49, v48, v47
	v_add_u32_e32 v47, 0x12900, v0
	v_cvt_pk_bf16_f32 v46, v46, v49
	ds_write_b16 v47, v46
	v_add_u32_e32 v47, 0x12a10, v0
	ds_write_b16_d16_hi v47, v46
	v_mov_b64_e32 v[46:47], v[186:187]
	v_mov_b64_e32 v[48:49], v[236:237]
	v_mul_f32_e32 v50, v61, v55
	v_lshlrev_b32_e32 v61, 16, v18
	v_and_b32_e32 v62, 0xffff0000, v18
	s_waitcnt vmcnt(0)
	v_fma_f32 v46, v50, v46, v48
	v_mul_f32_e32 v48, v60, v55
	v_fmac_f32_e32 v49, v48, v47
	v_add_u32_e32 v47, 0x12b20, v0
	v_cvt_pk_bf16_f32 v46, v46, v49
	ds_write_b16 v47, v46
	v_add_u32_e32 v47, 0x12c30, v0
	ds_write_b16_d16_hi v47, v46
	v_mov_b64_e32 v[46:47], v[188:189]
	v_mov_b64_e32 v[48:49], v[238:239]
	v_mul_f32_e32 v50, v59, v55
	v_lshlrev_b32_e32 v60, 16, v19
	v_and_b32_e32 v59, 0xffff0000, v19
	s_waitcnt vmcnt(0)
	v_fma_f32 v46, v50, v46, v48
	v_mul_f32_e32 v48, v58, v55
	v_fmac_f32_e32 v49, v48, v47
	v_add_u32_e32 v47, 0x12d40, v0
	v_cvt_pk_bf16_f32 v46, v46, v49
	ds_write_b16 v47, v46
	v_add_u32_e32 v47, 0x12e50, v0
	ds_write_b16_d16_hi v47, v46
	v_mov_b64_e32 v[46:47], v[190:191]
	v_mov_b64_e32 v[48:49], v[240:241]
	v_mul_f32_e32 v50, v57, v55
	v_lshlrev_b32_e32 v58, 16, v20
	v_and_b32_e32 v57, 0xffff0000, v20
	s_waitcnt vmcnt(0)
	v_fma_f32 v46, v50, v46, v48
	v_mul_f32_e32 v48, v56, v55
	v_fmac_f32_e32 v49, v48, v47
	v_add_u32_e32 v47, 0x12f60, v0
	v_cvt_pk_bf16_f32 v46, v46, v49
	ds_write_b16 v47, v46
	v_add_u32_e32 v47, 0x13070, v0
	ds_write_b16_d16_hi v47, v46
	v_mov_b64_e32 v[46:47], v[192:193]
	v_mov_b64_e32 v[48:49], v[242:243]
	v_and_b32_e32 v50, 0xffff0000, v15
	v_lshlrev_b32_e32 v15, 16, v6
	v_and_b32_e32 v6, 0xffff0000, v9
	v_lshlrev_b32_e32 v56, 16, v21
	v_and_b32_e32 v55, 0xffff0000, v21
	v_mul_f32_e32 v88, 0x3d372713, v6
	v_fma_f32 v88, v88, v6, 1.0
	s_waitcnt vmcnt(0)
	v_fma_f32 v45, v45, v46, v48
	v_fmac_f32_e32 v49, v44, v47
	v_cvt_pk_bf16_f32 v44, v45, v49
	v_add_u32_e32 v45, 0x13180, v0
	ds_write_b16 v45, v44
	v_add_u32_e32 v45, 0x13290, v0
	ds_write_b16_d16_hi v45, v44
	v_mov_b64_e32 v[44:45], v[194:195]
	v_mov_b64_e32 v[46:47], v[244:245]
	v_lshlrev_b32_e32 v49, 16, v16
	v_and_b32_e32 v48, 0xffff0000, v16
	s_waitcnt vmcnt(0)
	v_fma_f32 v43, v43, v44, v46
	v_fmac_f32_e32 v47, v42, v45
	v_cvt_pk_bf16_f32 v42, v43, v47
	v_add_u32_e32 v43, 0x133a0, v0
	ds_write_b16 v43, v42
	v_add_u32_e32 v43, 0x134b0, v0
	ds_write_b16_d16_hi v43, v42
	v_mov_b64_e32 v[42:43], v[196:197]
	v_mov_b64_e32 v[44:45], v[200:201]
	v_lshlrev_b32_e32 v47, 16, v17
	v_and_b32_e32 v46, 0xffff0000, v17
	v_mul_f32_e32 v17, 0x3d372713, v14
	v_fma_f32 v17, v17, v14, 1.0
	s_waitcnt vmcnt(0)
; __device__ __forceinline__ unsigned cvt_pk_bf16(float lo, float hi) { unsigned r; asm volatile("v_cvt_pk_bf16_f32 %0, %1, %2" : "=v"(r) : "v"(lo), "v"(hi)); return r; }
; __device__ __forceinline__ float gelu_f(float x) { const float y2 = 1.5957691216057308f * x * (1.0f + 0.044715f * x * x); return x * sigmoid_f(y2); }
; #define LAS __attribute__((address_space(3)))
; __device__ __forceinline__ void p2_block(LAS unsigned char* lds, const bf16_t* __restrict__ PROJ, bf16_t* __restrict__ ATT, bf16_t* __restrict__ SGU, const float* __restrict__ qn, const float* __restrict__ kn, ...
;     ...
;         for (int j = 0; j < 32; ++j) { v[j] = gelu_f(v[j]); sm += v[j]; }
;         sm += __shfl_xor(sm, 1); sm += __shfl_xor(sm, 2);
;         const float mu = sm * (1.0f / 128.0f); float q = 0.f;
; #pragma unroll
;         for (int j = 0; j < 32; ++j) { v[j] -= mu; q += v[j] * v[j]; }
;         q += __shfl_xor(q, 1); q += __shfl_xor(q, 2);
;         const float rstd = rsqrtf(q * (1.0f / 128.0f) + pg8::EPS);
;         const float* gp = lng + gg * 128 + 32 * q4; const float* bp = lnb + gg * 128 + 32 * q4;
;         LAS unsigned char* dst = lds + (gi ? VN_OFF1 : VN_OFF0) + (32 * q4) * VN_STRIDE + sp_ * 2;
; #pragma unroll
;         for (int j = 0; j < 32; j += 2) { const unsigned pk = cvt_pk_bf16(v[j] * rstd * gp[j] + bp[j], v[j + 1] * rstd * gp[j + 1] + bp[j + 1]);
;             *(LAS unsigned short*)(dst + j * VN_STRIDE) = (unsigned short)(pk & 0xffffu); *(LAS unsigned short*)(dst + (j + 1) * VN_STRIDE) = (unsigned short)(pk >> 16); }
	v_fma_f32 v41, v41, v42, v44
	v_fmac_f32_e32 v45, v40, v43
	v_cvt_pk_bf16_f32 v40, v41, v45
	v_add_u32_e32 v41, 0x135c0, v0
	ds_write_b16 v41, v40
	v_add_u32_e32 v41, 0x136d0, v0
	ds_write_b16_d16_hi v41, v40
	v_mov_b64_e32 v[40:41], v[198:199]
	v_mov_b64_e32 v[42:43], v[202:203]
	v_lshlrev_b32_e32 v45, 16, v10
	v_and_b32_e32 v44, 0xffff0000, v10
	v_and_b32_e32 v10, 0xffff0000, v8
	s_waitcnt vmcnt(0)
	global_load_dwordx4 v[144:147], v182, s[36:37] offset:512
	global_load_dwordx4 v[148:151], v182, s[36:37] offset:528
	global_load_dwordx4 v[152:155], v182, s[36:37] offset:544
	global_load_dwordx4 v[156:159], v182, s[36:37] offset:560
	global_load_dwordx4 v[184:187], v182, s[36:37] offset:576
	global_load_dwordx4 v[188:191], v182, s[36:37] offset:592
	global_load_dwordx4 v[192:195], v182, s[36:37] offset:608
	global_load_dwordx4 v[196:199], v182, s[36:37] offset:624
	global_load_dwordx4 v[218:221], v182, s[18:19] offset:512
	global_load_dwordx4 v[222:225], v182, s[18:19] offset:528
	global_load_dwordx4 v[226:229], v182, s[18:19] offset:544
	global_load_dwordx4 v[230:233], v182, s[18:19] offset:560
	global_load_dwordx4 v[234:237], v182, s[18:19] offset:576
	global_load_dwordx4 v[238:241], v182, s[18:19] offset:592
	global_load_dwordx4 v[242:245], v182, s[18:19] offset:608
	global_load_dwordx4 v[200:203], v182, s[18:19] offset:624
	v_fma_f32 v39, v39, v40, v42
	v_fmac_f32_e32 v43, v38, v41
	v_cvt_pk_bf16_f32 v38, v39, v43
	v_add_u32_e32 v39, 0x137e0, v0
	ds_write_b16 v39, v38
	v_add_u32_e32 v39, 0x138f0, v0
	ds_write_b16_d16_hi v39, v38
	v_lshlrev_b32_e32 v41, 16, v12
	v_and_b32_e32 v40, 0xffff0000, v12
	v_lshlrev_b32_e32 v39, 16, v13
	v_and_b32_e32 v38, 0xffff0000, v13
	v_lshlrev_b32_e32 v13, 16, v7
	v_and_b32_e32 v12, 0xffff0000, v7
	v_lshlrev_b32_e32 v7, 16, v9
	v_mul_f32_e32 v9, 0x3d372713, v61
	v_lshlrev_b32_e32 v43, 16, v11
	v_and_b32_e32 v42, 0xffff0000, v11
	v_lshlrev_b32_e32 v11, 16, v8
	v_mul_f32_e32 v8, 0x3fcc422a, v61
	v_fma_f32 v9, v9, v61, 1.0
	v_mul_f32_e32 v8, v8, v9
	v_mul_f32_e32 v8, 0xbfb8aa3b, v8
	v_exp_f32_e32 v8, v8
	v_mul_f32_e32 v9, 0x3d372713, v62
	v_fma_f32 v9, v9, v62, 1.0
	v_add_f32_e32 v8, 1.0, v8
	v_rcp_f32_e32 v63, v8
	v_mul_f32_e32 v8, 0x3fcc422a, v62
	v_mul_f32_e32 v8, v8, v9
	v_mul_f32_e32 v8, 0xbfb8aa3b, v8
	v_exp_f32_e32 v8, v8
	v_mul_f32_e32 v9, 0x3d372713, v60
	v_fma_f32 v9, v9, v60, 1.0
	v_fma_f32 v16, v63, v61, 0
	v_add_f32_e32 v8, 1.0, v8
	v_rcp_f32_e32 v64, v8
	v_mul_f32_e32 v8, 0x3fcc422a, v60
	v_mul_f32_e32 v8, v8, v9
	v_mul_f32_e32 v8, 0xbfb8aa3b, v8
	v_exp_f32_e32 v8, v8
	v_mul_f32_e32 v9, 0x3d372713, v59
	v_fma_f32 v9, v9, v59, 1.0
	v_fmac_f32_e32 v16, v64, v62
	v_add_f32_e32 v8, 1.0, v8
	v_rcp_f32_e32 v65, v8
	v_mul_f32_e32 v8, 0x3fcc422a, v59
	v_mul_f32_e32 v8, v8, v9
	v_mul_f32_e32 v8, 0xbfb8aa3b, v8
	v_exp_f32_e32 v8, v8
	v_mul_f32_e32 v9, 0x3d372713, v58
	v_fma_f32 v9, v9, v58, 1.0
	v_fmac_f32_e32 v16, v65, v60
	v_add_f32_e32 v8, 1.0, v8
	v_rcp_f32_e32 v66, v8
	v_mul_f32_e32 v8, 0x3fcc422a, v58
	v_mul_f32_e32 v8, v8, v9
	v_mul_f32_e32 v8, 0xbfb8aa3b, v8
	v_exp_f32_e32 v8, v8
	v_mul_f32_e32 v9, 0x3d372713, v57
	v_fma_f32 v9, v9, v57, 1.0
	v_fmac_f32_e32 v16, v66, v59
	v_add_f32_e32 v8, 1.0, v8
	v_rcp_f32_e32 v67, v8
	v_mul_f32_e32 v8, 0x3fcc422a, v57
	v_mul_f32_e32 v8, v8, v9
	v_mul_f32_e32 v8, 0xbfb8aa3b, v8
	v_exp_f32_e32 v8, v8
	v_mul_f32_e32 v9, 0x3d372713, v56
	v_fma_f32 v9, v9, v56, 1.0
	v_fmac_f32_e32 v16, v67, v58
	v_add_f32_e32 v8, 1.0, v8
	v_rcp_f32_e32 v68, v8
	v_mul_f32_e32 v8, 0x3fcc422a, v56
	v_mul_f32_e32 v8, v8, v9
	v_mul_f32_e32 v8, 0xbfb8aa3b, v8
	v_exp_f32_e32 v8, v8
	v_mul_f32_e32 v9, 0x3d372713, v55
	v_fma_f32 v9, v9, v55, 1.0
	v_fmac_f32_e32 v16, v68, v57
	v_add_f32_e32 v8, 1.0, v8
	v_rcp_f32_e32 v69, v8
	v_mul_f32_e32 v8, 0x3fcc422a, v55
	v_mul_f32_e32 v8, v8, v9
	v_mul_f32_e32 v8, 0xbfb8aa3b, v8
	v_exp_f32_e32 v8, v8
	v_mul_f32_e32 v9, 0x3d372713, v53
	v_fma_f32 v9, v9, v53, 1.0
	v_fmac_f32_e32 v16, v69, v56
	v_add_f32_e32 v8, 1.0, v8
	v_rcp_f32_e32 v70, v8
	v_mul_f32_e32 v8, 0x3fcc422a, v53
	v_mul_f32_e32 v8, v8, v9
	v_mul_f32_e32 v8, 0xbfb8aa3b, v8
	v_exp_f32_e32 v8, v8
	v_mul_f32_e32 v9, 0x3d372713, v52
	v_fma_f32 v9, v9, v52, 1.0
	v_fmac_f32_e32 v16, v70, v55
	v_add_f32_e32 v8, 1.0, v8
	v_rcp_f32_e32 v71, v8
	v_mul_f32_e32 v8, 0x3fcc422a, v52
	v_mul_f32_e32 v8, v8, v9
	v_mul_f32_e32 v8, 0xbfb8aa3b, v8
	v_exp_f32_e32 v8, v8
	v_mul_f32_e32 v9, 0x3d372713, v51
	v_fma_f32 v9, v9, v51, 1.0
	v_fmac_f32_e32 v16, v71, v53
	v_add_f32_e32 v8, 1.0, v8
	v_rcp_f32_e32 v72, v8
	v_mul_f32_e32 v8, 0x3fcc422a, v51
	v_mul_f32_e32 v8, v8, v9
	v_mul_f32_e32 v8, 0xbfb8aa3b, v8
	v_exp_f32_e32 v8, v8
	v_mul_f32_e32 v9, 0x3d372713, v50
	v_fma_f32 v9, v9, v50, 1.0
	v_fmac_f32_e32 v16, v72, v52
	v_add_f32_e32 v8, 1.0, v8
	v_rcp_f32_e32 v73, v8
	v_mul_f32_e32 v8, 0x3fcc422a, v50
	v_mul_f32_e32 v8, v8, v9
	v_mul_f32_e32 v8, 0xbfb8aa3b, v8
	v_exp_f32_e32 v8, v8
	v_mul_f32_e32 v9, 0x3d372713, v49
	v_fma_f32 v9, v9, v49, 1.0
	v_fmac_f32_e32 v16, v73, v51
	v_add_f32_e32 v8, 1.0, v8
	v_rcp_f32_e32 v74, v8
	v_mul_f32_e32 v8, 0x3fcc422a, v49
	v_mul_f32_e32 v8, v8, v9
	v_mul_f32_e32 v8, 0xbfb8aa3b, v8
	v_exp_f32_e32 v8, v8
	v_mul_f32_e32 v9, 0x3d372713, v48
	v_fma_f32 v9, v9, v48, 1.0
	v_fmac_f32_e32 v16, v74, v50
	v_add_f32_e32 v8, 1.0, v8
	v_rcp_f32_e32 v75, v8
	v_mul_f32_e32 v8, 0x3fcc422a, v48
	v_mul_f32_e32 v8, v8, v9
	v_mul_f32_e32 v8, 0xbfb8aa3b, v8
	v_exp_f32_e32 v8, v8
	v_mul_f32_e32 v9, 0x3d372713, v47
	v_fma_f32 v9, v9, v47, 1.0
	v_fmac_f32_e32 v16, v75, v49
	v_add_f32_e32 v8, 1.0, v8
	v_rcp_f32_e32 v76, v8
	v_mul_f32_e32 v8, 0x3fcc422a, v47
	v_mul_f32_e32 v8, v8, v9
	v_mul_f32_e32 v8, 0xbfb8aa3b, v8
; __device__ __forceinline__ float gelu_f(float x) { const float y2 = 1.5957691216057308f * x * (1.0f + 0.044715f * x * x); return x * sigmoid_f(y2); }
; __device__ __forceinline__ void p2_block(LAS unsigned char* lds, const bf16_t* __restrict__ PROJ, bf16_t* __restrict__ ATT, bf16_t* __restrict__ SGU, const float* __restrict__ qn, const float* __restrict__ kn, ...
;     ...
;         for (int j = 0; j < 32; ++j) { v[j] = gelu_f(v[j]); sm += v[j]; }
;         sm += __shfl_xor(sm, 1); sm += __shfl_xor(sm, 2);
	v_exp_f32_e32 v8, v8
	v_mul_f32_e32 v9, 0x3d372713, v46
	v_fma_f32 v9, v9, v46, 1.0
	v_fmac_f32_e32 v16, v76, v48
	v_add_f32_e32 v8, 1.0, v8
	v_rcp_f32_e32 v77, v8
	v_mul_f32_e32 v8, 0x3fcc422a, v46
	v_mul_f32_e32 v8, v8, v9
	v_mul_f32_e32 v8, 0xbfb8aa3b, v8
	v_exp_f32_e32 v8, v8
	v_mul_f32_e32 v9, 0x3d372713, v45
	v_fma_f32 v9, v9, v45, 1.0
	v_fmac_f32_e32 v16, v77, v47
	v_add_f32_e32 v8, 1.0, v8
	v_rcp_f32_e32 v78, v8
	v_mul_f32_e32 v8, 0x3fcc422a, v45
	v_mul_f32_e32 v8, v8, v9
	v_mul_f32_e32 v8, 0xbfb8aa3b, v8
	v_exp_f32_e32 v8, v8
	v_mul_f32_e32 v9, 0x3d372713, v44
	v_fma_f32 v9, v9, v44, 1.0
	v_fmac_f32_e32 v16, v78, v46
	v_add_f32_e32 v8, 1.0, v8
	v_rcp_f32_e32 v79, v8
	v_mul_f32_e32 v8, 0x3fcc422a, v44
	v_mul_f32_e32 v8, v8, v9
	v_mul_f32_e32 v8, 0xbfb8aa3b, v8
	v_exp_f32_e32 v8, v8
	v_mul_f32_e32 v9, 0x3d372713, v43
	v_fma_f32 v9, v9, v43, 1.0
	v_fmac_f32_e32 v16, v79, v45
	v_add_f32_e32 v8, 1.0, v8
	v_rcp_f32_e32 v80, v8
	v_mul_f32_e32 v8, 0x3fcc422a, v43
	v_mul_f32_e32 v8, v8, v9
	v_mul_f32_e32 v8, 0xbfb8aa3b, v8
	v_exp_f32_e32 v8, v8
	v_mul_f32_e32 v9, 0x3d372713, v42
	v_fma_f32 v9, v9, v42, 1.0
	v_fmac_f32_e32 v16, v80, v44
	v_add_f32_e32 v8, 1.0, v8
	v_rcp_f32_e32 v81, v8
	v_mul_f32_e32 v8, 0x3fcc422a, v42
	v_mul_f32_e32 v8, v8, v9
	v_mul_f32_e32 v8, 0xbfb8aa3b, v8
	v_exp_f32_e32 v8, v8
	v_mul_f32_e32 v9, 0x3d372713, v41
	v_fma_f32 v9, v9, v41, 1.0
	v_fmac_f32_e32 v16, v81, v43
	v_add_f32_e32 v8, 1.0, v8
	v_rcp_f32_e32 v82, v8
	v_mul_f32_e32 v8, 0x3fcc422a, v41
	v_mul_f32_e32 v8, v8, v9
	v_mul_f32_e32 v8, 0xbfb8aa3b, v8
	v_exp_f32_e32 v8, v8
	v_mul_f32_e32 v9, 0x3d372713, v40
	v_fma_f32 v9, v9, v40, 1.0
	v_fmac_f32_e32 v16, v82, v42
	v_add_f32_e32 v8, 1.0, v8
	v_rcp_f32_e32 v83, v8
	v_mul_f32_e32 v8, 0x3fcc422a, v40
	v_mul_f32_e32 v8, v8, v9
	v_mul_f32_e32 v8, 0xbfb8aa3b, v8
	v_exp_f32_e32 v8, v8
	v_mul_f32_e32 v9, 0x3d372713, v39
	v_fma_f32 v9, v9, v39, 1.0
	v_fmac_f32_e32 v16, v83, v41
	v_add_f32_e32 v8, 1.0, v8
	v_rcp_f32_e32 v84, v8
	v_mul_f32_e32 v8, 0x3fcc422a, v39
	v_mul_f32_e32 v8, v8, v9
	v_mul_f32_e32 v8, 0xbfb8aa3b, v8
	v_exp_f32_e32 v8, v8
	v_mul_f32_e32 v9, 0x3d372713, v38
	v_fma_f32 v9, v9, v38, 1.0
	v_fmac_f32_e32 v16, v84, v40
	v_add_f32_e32 v8, 1.0, v8
	v_rcp_f32_e32 v85, v8
	v_mul_f32_e32 v8, 0x3fcc422a, v38
	v_mul_f32_e32 v8, v8, v9
	v_mul_f32_e32 v8, 0xbfb8aa3b, v8
	v_exp_f32_e32 v8, v8
	v_mul_f32_e32 v9, 0x3d372713, v15
	v_fma_f32 v9, v9, v15, 1.0
	v_fmac_f32_e32 v16, v85, v39
	v_add_f32_e32 v8, 1.0, v8
	v_rcp_f32_e32 v86, v8
	v_mul_f32_e32 v8, 0x3fcc422a, v15
	v_mul_f32_e32 v8, v8, v9
	v_mul_f32_e32 v8, 0xbfb8aa3b, v8
	v_exp_f32_e32 v8, v8
	v_fmac_f32_e32 v16, v86, v38
	v_add_f32_e32 v8, 1.0, v8
	v_rcp_f32_e32 v9, v8
	v_mul_f32_e32 v8, 0x3fcc422a, v14
	v_mul_f32_e32 v8, v8, v17
	v_mul_f32_e32 v8, 0xbfb8aa3b, v8
	v_exp_f32_e32 v8, v8
	v_mul_f32_e32 v17, 0x3d372713, v13
	v_fma_f32 v17, v17, v13, 1.0
	v_add_f32_e32 v8, 1.0, v8
	v_rcp_f32_e32 v8, v8
	s_nop 0
	v_pk_mul_f32 v[18:19], v[8:9], v[14:15]
	s_nop 0
	v_add_f32_e32 v16, v19, v16
	v_add_f32_e32 v20, v18, v16
	v_mul_f32_e32 v16, 0x3fcc422a, v13
	v_mul_f32_e32 v16, v16, v17
	v_mul_f32_e32 v16, 0xbfb8aa3b, v16
	v_exp_f32_e32 v16, v16
	v_mul_f32_e32 v18, 0x3d372713, v12
	v_fma_f32 v18, v18, v12, 1.0
	v_add_f32_e32 v16, 1.0, v16
	v_rcp_f32_e32 v17, v16
	v_mul_f32_e32 v16, 0x3fcc422a, v12
	v_mul_f32_e32 v16, v16, v18
	v_mul_f32_e32 v16, 0xbfb8aa3b, v16
	v_exp_f32_e32 v16, v16
	s_nop 0
	v_add_f32_e32 v16, 1.0, v16
	v_rcp_f32_e32 v16, v16
	s_nop 0
	v_pk_mul_f32 v[18:19], v[16:17], v[12:13]
	s_nop 0
	v_add_f32_e32 v19, v19, v20
	v_add_f32_e32 v87, v18, v19
	v_mul_f32_e32 v19, 0x3d372713, v11
	v_mul_f32_e32 v18, 0x3fcc422a, v11
	v_fma_f32 v19, v19, v11, 1.0
	v_mul_f32_e32 v18, v18, v19
	v_mul_f32_e32 v18, 0xbfb8aa3b, v18
	v_exp_f32_e32 v18, v18
	v_mul_f32_e32 v20, 0x3d372713, v10
	v_fma_f32 v20, v20, v10, 1.0
	v_add_f32_e32 v18, 1.0, v18
	v_rcp_f32_e32 v19, v18
	v_mul_f32_e32 v18, 0x3fcc422a, v10
	v_mul_f32_e32 v18, v18, v20
	v_mul_f32_e32 v18, 0xbfb8aa3b, v18
	v_exp_f32_e32 v18, v18
	s_nop 0
	v_add_f32_e32 v18, 1.0, v18
	v_rcp_f32_e32 v18, v18
	s_nop 0
	v_pk_mul_f32 v[20:21], v[18:19], v[10:11]
	s_nop 0
	v_add_f32_e32 v21, v21, v87
	v_add_f32_e32 v87, v20, v21
	v_mul_f32_e32 v21, 0x3d372713, v7
	v_mul_f32_e32 v20, 0x3fcc422a, v7
	v_fma_f32 v21, v21, v7, 1.0
	v_mul_f32_e32 v20, v20, v21
	v_mul_f32_e32 v20, 0xbfb8aa3b, v20
	v_exp_f32_e32 v20, v20
	s_nop 0
	v_add_f32_e32 v20, 1.0, v20
	v_rcp_f32_e32 v21, v20
	v_mul_f32_e32 v20, 0x3fcc422a, v6
	v_mul_f32_e32 v20, v20, v88
	v_mul_f32_e32 v20, 0xbfb8aa3b, v20
	v_exp_f32_e32 v20, v20
	s_nop 0
	v_add_f32_e32 v20, 1.0, v20
	v_rcp_f32_e32 v20, v20
	s_nop 0
	v_pk_mul_f32 v[88:89], v[20:21], v[6:7]
	s_nop 0
	v_add_f32_e32 v87, v89, v87
	v_add_f32_e32 v87, v88, v87
	s_nop 1
	v_mov_b32_dpp v88, v87 quad_perm:[1,0,3,2] row_mask:0xf bank_mask:0xf
	s_waitcnt lgkmcnt(0)
	v_add_f32_e32 v87, v87, v88
	s_nop 1
	v_mov_b32_dpp v88, v87 quad_perm:[2,3,0,1] row_mask:0xf bank_mask:0xf
	s_waitcnt lgkmcnt(0)
; __device__ __forceinline__ unsigned cvt_pk_bf16(float lo, float hi) { unsigned r; asm volatile("v_cvt_pk_bf16_f32 %0, %1, %2" : "=v"(r) : "v"(lo), "v"(hi)); return r; }
; #define LAS __attribute__((address_space(3)))
; __device__ __forceinline__ void p2_block(LAS unsigned char* lds, const bf16_t* __restrict__ PROJ, bf16_t* __restrict__ ATT, bf16_t* __restrict__ SGU, const float* __restrict__ qn, const float* __restrict__ kn, ...
;     ...
;         const float mu = sm * (1.0f / 128.0f); float q = 0.f;
; #pragma unroll
;         for (int j = 0; j < 32; ++j) { v[j] -= mu; q += v[j] * v[j]; }
;         q += __shfl_xor(q, 1); q += __shfl_xor(q, 2);
;         const float rstd = rsqrtf(q * (1.0f / 128.0f) + pg8::EPS);
;         const float* gp = lng + gg * 128 + 32 * q4; const float* bp = lnb + gg * 128 + 32 * q4;
;         LAS unsigned char* dst = lds + (gi ? VN_OFF1 : VN_OFF0) + (32 * q4) * VN_STRIDE + sp_ * 2;
; #pragma unroll
;         for (int j = 0; j < 32; j += 2) { const unsigned pk = cvt_pk_bf16(v[j] * rstd * gp[j] + bp[j], v[j + 1] * rstd * gp[j + 1] + bp[j + 1]);
;             *(LAS unsigned short*)(dst + j * VN_STRIDE) = (unsigned short)(pk & 0xffffu); *(LAS unsigned short*)(dst + (j + 1) * VN_STRIDE) = (unsigned short)(pk >> 16); }
	v_add_f32_e32 v87, v87, v88
	v_mul_f32_e32 v88, 0x3c000000, v87
	v_fma_f32 v63, v63, v61, -v88
	v_fma_f32 v61, v64, v62, -v88
	v_mul_f32_e32 v62, v61, v61
	v_fmac_f32_e32 v62, v63, v63
	v_fma_f32 v60, v65, v60, -v88
	v_fmac_f32_e32 v62, v60, v60
	v_fma_f32 v59, v66, v59, -v88
	v_fmac_f32_e32 v62, v59, v59
	v_fma_f32 v58, v67, v58, -v88
	v_fmac_f32_e32 v62, v58, v58
	v_fma_f32 v57, v68, v57, -v88
	v_fmac_f32_e32 v62, v57, v57
	v_fma_f32 v56, v69, v56, -v88
	v_fmac_f32_e32 v62, v56, v56
	v_fma_f32 v55, v70, v55, -v88
	v_fmac_f32_e32 v62, v55, v55
	v_fma_f32 v53, v71, v53, -v88
	v_fmac_f32_e32 v62, v53, v53
	v_fma_f32 v52, v72, v52, -v88
	v_fmac_f32_e32 v62, v52, v52
	v_fma_f32 v51, v73, v51, -v88
	v_fmac_f32_e32 v62, v51, v51
	v_fma_f32 v50, v74, v50, -v88
	v_fmac_f32_e32 v62, v50, v50
	v_fma_f32 v49, v75, v49, -v88
	v_fmac_f32_e32 v62, v49, v49
	v_fma_f32 v48, v76, v48, -v88
	v_fmac_f32_e32 v62, v48, v48
	v_fma_f32 v47, v77, v47, -v88
	v_fmac_f32_e32 v62, v47, v47
	v_fma_f32 v46, v78, v46, -v88
	v_fmac_f32_e32 v62, v46, v46
	v_fma_f32 v45, v79, v45, -v88
	v_fmac_f32_e32 v62, v45, v45
	v_fma_f32 v44, v80, v44, -v88
	v_fmac_f32_e32 v62, v44, v44
	v_fma_f32 v43, v81, v43, -v88
	v_fmac_f32_e32 v62, v43, v43
	v_fma_f32 v42, v82, v42, -v88
	v_fmac_f32_e32 v62, v42, v42
	v_fma_f32 v41, v83, v41, -v88
	v_fmac_f32_e32 v62, v41, v41
	v_fma_f32 v40, v84, v40, -v88
	v_fmac_f32_e32 v62, v40, v40
	v_fma_f32 v39, v85, v39, -v88
	v_fmac_f32_e32 v62, v39, v39
	v_fma_f32 v38, v86, v38, -v88
	v_pk_fma_f32 v[14:15], v[8:9], v[14:15], v[88:89] op_sel_hi:[1,1,0] neg_lo:[0,0,1] neg_hi:[0,0,1]
	v_fmac_f32_e32 v62, v38, v38
	v_pk_mul_f32 v[8:9], v[14:15], v[14:15]
	v_pk_fma_f32 v[12:13], v[16:17], v[12:13], v[88:89] op_sel_hi:[1,1,0] neg_lo:[0,0,1] neg_hi:[0,0,1]
	v_add_f32_e32 v9, v9, v62
	v_add_f32_e32 v62, v8, v9
	v_pk_mul_f32 v[8:9], v[12:13], v[12:13]
	v_pk_fma_f32 v[6:7], v[20:21], v[6:7], v[88:89] op_sel_hi:[1,1,0] neg_lo:[0,0,1] neg_hi:[0,0,1]
	v_add_f32_e32 v9, v9, v62
	v_add_f32_e32 v16, v8, v9
	v_pk_fma_f32 v[8:9], v[18:19], v[10:11], v[88:89] op_sel_hi:[1,1,0] neg_lo:[0,0,1] neg_hi:[0,0,1]
	v_add_u32_e32 v19, 0x1a000, v0
	v_pk_mul_f32 v[10:11], v[8:9], v[8:9]
	v_lshlrev_b32_e32 v78, 16, v33
	v_add_f32_e32 v11, v11, v16
	v_add_f32_e32 v16, v10, v11
	v_pk_mul_f32 v[10:11], v[6:7], v[6:7]
	v_lshlrev_b32_e32 v79, 16, v5
	v_add_f32_e32 v11, v11, v16
	v_add_f32_e32 v10, v10, v11
	s_nop 1
	v_mov_b32_dpp v11, v10 quad_perm:[1,0,3,2] row_mask:0xf bank_mask:0xf
	v_and_b32_e32 v5, 0xffff0000, v4
	v_and_b32_e32 v4, 0xffff0000, v32
	v_mov_b32_e32 v32, v5
	v_mov_b32_e32 v33, v101
	s_waitcnt lgkmcnt(0)
	v_add_f32_e32 v10, v10, v11
	s_nop 1
	v_mov_b32_dpp v11, v10 quad_perm:[2,3,0,1] row_mask:0xf bank_mask:0xf
	v_mov_b32_e32 v54, v96
	v_add_u32_e32 v81, 0, v132
	v_lshlrev_b32_e32 v73, 2, v162
	v_sub_u32_e32 v74, v81, v130
	s_waitcnt lgkmcnt(0)
	v_add_f32_e32 v10, v10, v11
	v_fmamk_f32 v10, v10, 0x3c000000, v209
	v_cmp_gt_f32_e32 vcc, s82, v10
	v_mul_f32_e32 v11, 0x4b800000, v10
	v_or_b32_e32 v71, 2, v130
	v_cndmask_b32_e32 v10, v10, v11, vcc
	v_rsq_f32_e32 v10, v10
	v_or_b32_e32 v70, 3, v130
	v_or_b32_e32 v72, 4, v130
	v_mul_f32_e32 v11, 0x45800000, v10
	v_cndmask_b32_e32 v18, v10, v11, vcc
	s_waitcnt vmcnt(0)
	v_mov_b64_e32 v[10:11], v[144:145]
	v_mov_b64_e32 v[16:17], v[218:219]
	v_mul_f32_e32 v20, v63, v18
	v_mul_f32_e32 v15, v15, v18
	v_mul_f32_e32 v14, v14, v18
	v_mul_f32_e32 v13, v13, v18
	v_mul_f32_e32 v12, v12, v18
	v_mul_f32_e32 v9, v9, v18
	v_mul_f32_e32 v8, v8, v18
	v_mul_f32_e32 v7, v7, v18
	v_mul_f32_e32 v6, v6, v18
	s_waitcnt vmcnt(0)
	v_fma_f32 v10, v10, v20, v16
	v_mul_f32_e32 v16, v61, v18
	v_fmac_f32_e32 v17, v11, v16
	v_add_u32_e32 v11, 0x1a110, v0
	v_cvt_pk_bf16_f32 v10, v10, v17
	ds_write_b16 v19, v10
	ds_write_b16_d16_hi v11, v10
	v_mov_b64_e32 v[10:11], v[146:147]
	v_mov_b64_e32 v[16:17], v[220:221]
	v_mul_f32_e32 v19, v60, v18
	s_waitcnt vmcnt(0)
	v_fma_f32 v10, v10, v19, v16
	v_mul_f32_e32 v16, v59, v18
	v_fmac_f32_e32 v17, v11, v16
	v_add_u32_e32 v11, 0x1a220, v0
	v_cvt_pk_bf16_f32 v10, v10, v17
	ds_write_b16 v11, v10
	v_add_u32_e32 v11, 0x1a330, v0
	ds_write_b16_d16_hi v11, v10
	v_mov_b64_e32 v[10:11], v[148:149]
	v_mov_b64_e32 v[16:17], v[222:223]
	v_mul_f32_e32 v19, v58, v18
	s_waitcnt vmcnt(0)
	v_fma_f32 v10, v10, v19, v16
	v_mul_f32_e32 v16, v57, v18
	v_fmac_f32_e32 v17, v11, v16
	v_add_u32_e32 v11, 0x1a440, v0
	v_cvt_pk_bf16_f32 v10, v10, v17
	ds_write_b16 v11, v10
	v_add_u32_e32 v11, 0x1a550, v0
	ds_write_b16_d16_hi v11, v10
	v_mov_b64_e32 v[10:11], v[150:151]
	v_mov_b64_e32 v[16:17], v[224:225]
	v_mul_f32_e32 v19, v56, v18
	v_mov_b32_e32 v56, v109
	v_mov_b32_e32 v57, v105
	v_pk_fma_f32 v[110:111], v[56:57], v[56:57], v[110:111]
	s_waitcnt vmcnt(0)
	v_fma_f32 v10, v10, v19, v16
	v_mul_f32_e32 v16, v55, v18
	v_fmac_f32_e32 v17, v11, v16
	v_add_u32_e32 v11, 0x1a660, v0
	v_cvt_pk_bf16_f32 v10, v10, v17
	ds_write_b16 v11, v10
	v_add_u32_e32 v11, 0x1a770, v0
	ds_write_b16_d16_hi v11, v10
	v_mov_b64_e32 v[10:11], v[152:153]
	v_mov_b64_e32 v[16:17], v[226:227]
	v_mul_f32_e32 v19, v53, v18
	v_mov_b32_e32 v55, v78
	v_pk_mul_f32 v[54:55], v[54:55], v[54:55]
	s_waitcnt vmcnt(0)
	v_fma_f32 v10, v10, v19, v16
	v_mul_f32_e32 v16, v52, v18
	v_fmac_f32_e32 v17, v11, v16
	v_add_u32_e32 v11, 0x1a880, v0
	v_cvt_pk_bf16_f32 v10, v10, v17
	ds_write_b16 v11, v10
	v_add_u32_e32 v11, 0x1a990, v0
	ds_write_b16_d16_hi v11, v10
	v_mov_b64_e32 v[10:11], v[154:155]
	v_mov_b64_e32 v[16:17], v[228:229]
	v_mul_f32_e32 v19, v51, v18
	s_waitcnt vmcnt(0)
; __device__ __forceinline__ unsigned cvt_pk_bf16(float lo, float hi) { unsigned r; asm volatile("v_cvt_pk_bf16_f32 %0, %1, %2" : "=v"(r) : "v"(lo), "v"(hi)); return r; }
; #define LAS __attribute__((address_space(3)))
; __device__ __forceinline__ void unpack8(const u32x4 w, float* f) { f[0] = bf_lo(w.x); f[1] = bf_hi(w.x); f[2] = bf_lo(w.y); f[3] = bf_hi(w.y); f[4] = bf_lo(w.z); f[5] = bf_hi(w.z); f[6] = bf_lo(w.w); f[7] = bf_hi(w.w); }
; __device__ __forceinline__ void p2_block(LAS unsigned char* lds, const bf16_t* __restrict__ PROJ, bf16_t* __restrict__ ATT, bf16_t* __restrict__ SGU, const float* __restrict__ qn, const float* __restrict__ kn, ...
;     ...
;         for (int j = 0; j < 32; j += 2) { const unsigned pk = cvt_pk_bf16(v[j] * rstd * gp[j] + bp[j], v[j + 1] * rstd * gp[j + 1] + bp[j + 1]);
;             *(LAS unsigned short*)(dst + j * VN_STRIDE) = (unsigned short)(pk & 0xffffu); *(LAS unsigned short*)(dst + (j + 1) * VN_STRIDE) = (unsigned short)(pk >> 16); }
;     }
;     __syncthreads();
; #pragma unroll
;     for (int c = 2; c < 4; ++c) { const bf16_t* qp = PROJ + ((size_t)b * pg8::SEQ + n * 128 + rbase + 16 * c + fr) * pg8::IN_W + hq * 64 + 8 * fq; qa[c] = *(const u32x4*)qp; qb[c] = *(const u32x4*)(qp + 32); }
;     const float sink = sinks[hq];
;     constexpr float LOG2E = 1.4426950408889634f;
; #pragma unroll
;     for (int c = 0; c < 4; ++c) {
;         const int i0 = rbase + 16 * c, irow = i0 + fr, pos = n * 128 + irow; const size_t grow = (size_t)b * pg8::SEQ + pos;
;         bf16x8 qf0, qf1;
;         {
;             float x1[8], x2[8]; unpack8(qa[c], x1); unpack8(qb[c], x2);
;             float ss = 0.f;
; #pragma unroll
;             for (int j = 0; j < 8; ++j) ss += x1[j] * x1[j] + x2[j] * x2[j];
;             ss += __shfl_xor(ss, 16); ss += __shfl_xor(ss, 32);
;             const float rinv = rsqrtf(ss * (1.0f / 64.0f) + pg8::EPS) * 0.125f;
;             const float* cp = COS + pos * 32 + 8 * fq; const float* sp = SIN + pos * 32 + 8 * fq;
;             float o1[8], o2[8];
; #pragma unroll
;             for (int j = 0; j < 8; ++j) { const float a1 = x1[j] * rinv * qn[8 * fq + j], a2 = x2[j] * rinv * qn[32 + 8 * fq + j], cc = cp[j], sn = sp[j]; o1[j] = a1 * cc - a2 * sn; o2[j] = a2 * cc + a1 * sn; }
	v_fma_f32 v10, v10, v19, v16
	v_mul_f32_e32 v16, v50, v18
	v_fmac_f32_e32 v17, v11, v16
	v_add_u32_e32 v11, 0x1aaa0, v0
	v_cvt_pk_bf16_f32 v10, v10, v17
	ds_write_b16 v11, v10
	v_add_u32_e32 v11, 0x1abb0, v0
	ds_write_b16_d16_hi v11, v10
	v_mov_b64_e32 v[10:11], v[156:157]
	v_mov_b64_e32 v[16:17], v[230:231]
	v_mul_f32_e32 v19, v49, v18
	s_waitcnt vmcnt(0)
	v_fma_f32 v10, v10, v19, v16
	v_mul_f32_e32 v16, v48, v18
	v_fmac_f32_e32 v17, v16, v11
	v_add_u32_e32 v11, 0x1acc0, v0
	v_cvt_pk_bf16_f32 v10, v10, v17
	ds_write_b16 v11, v10
	v_add_u32_e32 v11, 0x1add0, v0
	ds_write_b16_d16_hi v11, v10
	v_mov_b64_e32 v[10:11], v[158:159]
	v_mov_b64_e32 v[16:17], v[232:233]
	v_mul_f32_e32 v19, v47, v18
	s_waitcnt vmcnt(0)
	v_fma_f32 v10, v19, v10, v16
	v_mul_f32_e32 v16, v46, v18
	v_fmac_f32_e32 v17, v16, v11
	v_add_u32_e32 v11, 0x1aee0, v0
	v_cvt_pk_bf16_f32 v10, v10, v17
	ds_write_b16 v11, v10
	v_add_u32_e32 v11, 0x1aff0, v0
	ds_write_b16_d16_hi v11, v10
	v_mov_b64_e32 v[10:11], v[184:185]
	v_mov_b64_e32 v[16:17], v[234:235]
	v_mul_f32_e32 v19, v45, v18
	s_waitcnt vmcnt(0)
	v_fma_f32 v10, v19, v10, v16
	v_mul_f32_e32 v16, v44, v18
	v_fmac_f32_e32 v17, v16, v11
	v_add_u32_e32 v11, 0x1b100, v0
	v_cvt_pk_bf16_f32 v10, v10, v17
	ds_write_b16 v11, v10
	v_add_u32_e32 v11, 0x1b210, v0
	ds_write_b16_d16_hi v11, v10
	v_mov_b64_e32 v[10:11], v[186:187]
	v_mov_b64_e32 v[16:17], v[236:237]
	v_mul_f32_e32 v19, v43, v18
	v_or_b32_e32 v44, s17, v161
	s_waitcnt vmcnt(0)
	v_fma_f32 v10, v19, v10, v16
	v_mul_f32_e32 v16, v42, v18
	v_fmac_f32_e32 v17, v16, v11
	v_add_u32_e32 v11, 0x1b320, v0
	v_cvt_pk_bf16_f32 v10, v10, v17
	ds_write_b16 v11, v10
	v_add_u32_e32 v11, 0x1b430, v0
	ds_write_b16_d16_hi v11, v10
	v_mov_b64_e32 v[10:11], v[188:189]
	v_mov_b64_e32 v[16:17], v[238:239]
	v_mul_f32_e32 v19, v41, v18
	s_waitcnt vmcnt(0)
	v_fma_f32 v10, v19, v10, v16
	v_mul_f32_e32 v16, v40, v18
	v_fmac_f32_e32 v17, v16, v11
	v_add_u32_e32 v11, 0x1b540, v0
	v_cvt_pk_bf16_f32 v10, v10, v17
	ds_write_b16 v11, v10
	v_add_u32_e32 v11, 0x1b650, v0
	ds_write_b16_d16_hi v11, v10
	v_mov_b64_e32 v[10:11], v[190:191]
	v_mov_b64_e32 v[16:17], v[240:241]
	v_mul_f32_e32 v19, v39, v18
	s_waitcnt vmcnt(0)
	v_fma_f32 v10, v19, v10, v16
	v_mul_f32_e32 v16, v38, v18
	v_fmac_f32_e32 v17, v16, v11
	v_add_u32_e32 v11, 0x1b760, v0
	v_cvt_pk_bf16_f32 v10, v10, v17
	ds_write_b16 v11, v10
	v_add_u32_e32 v11, 0x1b870, v0
	ds_write_b16_d16_hi v11, v10
	v_mov_b64_e32 v[10:11], v[192:193]
	v_mov_b64_e32 v[16:17], v[242:243]
	s_waitcnt vmcnt(0)
	v_fma_f32 v10, v15, v10, v16
	v_fmac_f32_e32 v17, v14, v11
	v_add_u32_e32 v11, 0x1b980, v0
	v_cvt_pk_bf16_f32 v10, v10, v17
	ds_write_b16 v11, v10
	v_add_u32_e32 v11, 0x1ba90, v0
	ds_write_b16_d16_hi v11, v10
	v_mov_b64_e32 v[10:11], v[194:195]
	v_mov_b64_e32 v[14:15], v[244:245]
	s_waitcnt vmcnt(0)
	v_fma_f32 v10, v13, v10, v14
	v_fmac_f32_e32 v15, v12, v11
	v_add_u32_e32 v11, 0x1bba0, v0
	v_cvt_pk_bf16_f32 v10, v10, v15
	ds_write_b16 v11, v10
	v_add_u32_e32 v11, 0x1bcb0, v0
	ds_write_b16_d16_hi v11, v10
	v_mov_b64_e32 v[10:11], v[196:197]
	v_mov_b64_e32 v[12:13], v[200:201]
	v_lshlrev_b32_e32 v14, 7, v44
	v_mov_b32_e32 v15, v1
	v_or_b32_e32 v44, s48, v44
	s_waitcnt vmcnt(0)
	v_fma_f32 v9, v9, v10, v12
	v_fmac_f32_e32 v13, v8, v11
	v_cvt_pk_bf16_f32 v8, v9, v13
	v_add_u32_e32 v9, 0x1bdc0, v0
	ds_write_b16 v9, v8
	v_add_u32_e32 v9, 0x1bed0, v0
	ds_write_b16_d16_hi v9, v8
	v_mov_b64_e32 v[8:9], v[198:199]
	v_mov_b64_e32 v[10:11], v[202:203]
	s_waitcnt vmcnt(0)
	v_fma_f32 v7, v7, v8, v10
	v_fmac_f32_e32 v11, v6, v9
	v_cvt_pk_bf16_f32 v6, v7, v11
	v_add_u32_e32 v7, 0x1bfe0, v0
	v_add_u32_e32 v0, 0x1c0f0, v0
	ds_write_b16_d16_hi v0, v6
	v_or_b32_e32 v0, 32, v163
	ds_write_b16 v7, v6
	v_mad_u64_u32 v[6:7], s[28:29], v0, s83, v[134:135]
	v_mad_i32_i24 v7, s49, v212, v7
	v_or_b32_e32 v0, 48, v163
	v_readfirstlane_b32 s16, v204
	v_and_b32_e32 v43, 15, v204
	v_bfe_u32 v44, v204, 4, 2
	s_and_b32 s24, s2, 3
	s_lshr_b32 s16, s16, 6
	s_bfe_u32 s27, s2, 0x40002
	s_lshr_b32 s17, s16, 1
	s_and_b32 s25, s16, 1
	s_lshl_b32 s25, s25, 6
	s_lshl_b32 s26, s24, 2
	s_add_i32 s26, s26, s17
	s_and_b32 s28, s2, -4
	s_lshl_b32 s28, s28, 5
	s_lshl_b32 s29, s27, 7
	s_add_i32 s28, s28, s25
	s_add_i32 s29, s29, s25
	s_lshl_b32 s4, s26, 7
	v_add_u32_e32 v166, s28, v43
	v_mul_u32_u24_e32 v46, 0x3c00, v166
	v_lshl_add_u32 v46, v44, 4, v46
	v_add_u32_e32 v46, s4, v46
	v_lshlrev_b32_e32 v48, 11, v166
	v_lshl_add_u32 v48, v44, 3, v48
	v_add_u32_e32 v48, s4, v48
	v_add_u32_e32 v166, s29, v43
	v_lshlrev_b32_e32 v47, 7, v166
	v_lshl_add_u32 v47, v44, 5, v47
	v_mul_u32_u24_e32 v45, 0x90, v43
	v_lshl_add_u32 v45, v44, 4, v45
	v_mul_u32_u24_e32 v166, 0x210, v43
	v_lshl_add_u32 v166, v44, 3, v166
	v_add_u32_e32 v194, 0x9000, v166
	v_add_u32_e32 v195, 0xb100, v166
	v_add_u32_e32 v196, 0xd200, v166
	v_add_u32_e32 v197, 0xf300, v166
	v_lshlrev_b32_e32 v166, 2, v44
	v_sub_u32_e32 v166, v43, v166
	v_cmp_gt_i32_e64 s[40:41], 0, v166
	v_cmp_gt_i32_e64 s[42:43], 1, v166
	v_cmp_gt_i32_e64 s[44:45], 2, v166
	v_cmp_gt_i32_e64 s[46:47], 3, v166
	v_mov_b32_e32 v49, 0xf149f2ca
	v_lshlrev_b32_e32 v167, 5, v44
	v_mov_b32_e32 v166, s26
	v_lshlrev_b32_e32 v166, 2, v166
	s_mov_b32 s4, s25
	s_mov_b32 vcc_lo, s63
	s_mov_b32 vcc_hi, s78
	s_cmp_lg_u32 s27, 0
	s_cselect_b64 s[28:29], -1, 0
	s_and_b64 s[48:49], s[40:41], s[28:29]
	s_and_b64 s[50:51], s[42:43], s[28:29]
	s_and_b64 s[52:53], s[44:45], s[28:29]
	s_and_b64 s[26:27], s[46:47], s[28:29]
	v_readlane_b32 s6, v250, 36
	v_readlane_b32 s7, v250, 37
	v_readlane_b32 s16, v250, 38
	v_readlane_b32 s17, v250, 39
	v_readlane_b32 s24, v248, 54
	v_readlane_b32 s25, v248, 55
	global_load_dwordx4 v[26:29], v167, s[38:39]
	global_load_dwordx4 v[30:33], v167, s[38:39] offset:16
	global_load_dwordx4 v[34:37], v167, s[38:39] offset:128
	global_load_dwordx4 v[38:41], v167, s[38:39] offset:144
	global_load_dword v42, v166, vcc
	s_nop 1
	global_load_dwordx4 v[2:5], v46, s[10:11]
	global_load_dwordx4 v[6:9], v46, s[10:11] offset:64
	global_load_dwordx4 v[10:13], v47, s[6:7]
	global_load_dwordx4 v[14:17], v47, s[6:7] offset:16
	global_load_dwordx4 v[18:21], v47, s[16:17]
	global_load_dwordx4 v[22:25], v47, s[16:17] offset:16
	v_add_u32_e32 v46, 0x3c000, v46
	v_add_u32_e32 v47, 0x800, v47
	global_load_dwordx4 v[218:221], v46, s[10:11]
	global_load_dwordx4 v[222:225], v46, s[10:11] offset:64
	global_load_dwordx4 v[226:229], v47, s[6:7]
	global_load_dwordx4 v[230:233], v47, s[6:7] offset:16
	global_load_dwordx4 v[234:237], v47, s[16:17]
	global_load_dwordx4 v[238:241], v47, s[16:17] offset:16
	v_add_u32_e32 v46, 0x3c000, v46
	v_add_u32_e32 v47, 0x800, v47
	s_waitcnt lgkmcnt(0)
	s_barrier
	s_cmp_eq_u32 s4, 0
	s_cbranch_scc1 .Latt_r0

; __device__ __forceinline__ unsigned cvt_pk_bf16(float lo, float hi) { unsigned r; asm volatile("v_cvt_pk_bf16_f32 %0, %1, %2" : "=v"(r) : "v"(lo), "v"(hi)); return r; }
; __device__ __forceinline__ void st16_wt(void* p, u32x4 v) { asm volatile("global_store_dwordx4 %0, %1, off sc1\n\ts_nop 1" :: "v"(p), "v"(v) : "memory"); }
; __device__ __forceinline__ void tr_item(const float* __restrict__ W, int K, int N, bf16_t* WT, const float* __restrict__ kscale, int rowmode, int item, int lane) {
;     const int nblk = N >> 5, kb = item / nblk, nb = item - kb * nblk;
;     const int c = lane >> 3, q = lane & 7, k0 = kb * 64 + c * 8, n0 = nb * 32 + q * 4;
;     f32x4 v[8];
; #pragma unroll
;     for (int i = 0; i < 8; ++i) v[i] = __builtin_nontemporal_load((const f32x4*)(W + (size_t)(k0 + i) * N + n0));
;     if (kscale) { const f32x4 s0 = *(const f32x4*)(kscale + k0), s1 = *(const f32x4*)(kscale + k0 + 4);
; #pragma unroll
;         for (int i = 0; i < 4; ++i) { v[i] = v[i] * s0[i]; v[4 + i] = v[4 + i] * s1[i]; } }
;     int drow;
;     if (rowmode == 0) drow = n0;
;     else if (rowmode == 3) { const int g = n0 - pg8::C_GA; drow = g < 0 ? n0 : pg8::C_GA + (((g & 2047) >> 7) << 8) + ((g >> 11) << 7) + (g & 127); }
;     else drow = ((n0 >> 7) << 8) + (n0 & 127) + (rowmode == 2 ? 128 : 0);
; #pragma unroll
;     for (int e = 0; e < 4; ++e) { u32x4 o; o.x = cvt_pk_bf16(v[0][e], v[1][e]); o.y = cvt_pk_bf16(v[2][e], v[3][e]); o.z = cvt_pk_bf16(v[4][e], v[5][e]); o.w = cvt_pk_bf16(v[6][e], v[7][e]);
;         pg8::st16_wt(WT + (size_t)(drow + e) * K + k0, o); }
.LBB0_400:
	s_or_b64 exec, exec, s[0:1]
	v_readfirstlane_b32 vcc_lo, v204
	s_nop 3
	s_lshr_b32 vcc_lo, vcc_lo, 6
	s_cmp_eq_u32 vcc_lo, 0
	s_cbranch_scc1 .Lcv_skip_2
	s_lshr_b32 m0, s85, 5
	v_subrev_u32_e32 v106, 64, v204
	v_mov_b32_e32 v107, m0
	v_lshlrev_b32_e32 v107, 8, v107
	v_mov_b32_e32 v108, v106
	v_lshrrev_b32_e32 v109, 3, v108
	v_add_u32_e32 v109, v109, v107
	v_mul_u32_u24_e32 v109, 0x800, v109
	v_and_b32_e32 v108, 7, v108
	v_lshl_add_u32 v109, v108, 6, v109
	v_add_u32_e32 v108, 448, v106
	v_lshrrev_b32_e32 v110, 3, v108
	v_add_u32_e32 v110, v110, v107
	v_mul_u32_u24_e32 v110, 0x800, v110
	v_and_b32_e32 v108, 7, v108
	v_lshl_add_u32 v110, v108, 6, v110
	v_add_u32_e32 v108, 896, v106
	v_lshrrev_b32_e32 v111, 3, v108
	v_add_u32_e32 v111, v111, v107
	v_mul_u32_u24_e32 v111, 0x800, v111
	v_and_b32_e32 v108, 7, v108
	v_lshl_add_u32 v111, v108, 6, v111
	v_add_u32_e32 v108, 1344, v106
	v_lshrrev_b32_e32 v112, 3, v108
	v_add_u32_e32 v112, v112, v107
	v_mul_u32_u24_e32 v112, 0x800, v112
	v_and_b32_e32 v108, 7, v108
	v_lshl_add_u32 v112, v108, 6, v112
	v_add_u32_e32 v108, 1792, v106
	v_and_b32_e32 v108, 0x7ff, v108
	v_lshrrev_b32_e32 v113, 3, v108
	v_add_u32_e32 v113, v113, v107
	v_mul_u32_u24_e32 v113, 0x800, v113
	v_and_b32_e32 v108, 7, v108
	v_lshl_add_u32 v113, v108, 6, v113
	v_readlane_b32 vcc_lo, v250, 36
	v_readlane_b32 vcc_hi, v250, 37
	s_nop 3
	s_add_u32 vcc_lo, vcc_lo, 0x3dc0000
	s_addc_u32 vcc_hi, vcc_hi, 0
	s_cmp_lg_u32 s64, 0
	s_cselect_b32 m0, 0x400000, 0
	s_add_u32 vcc_lo, vcc_lo, m0
	s_addc_u32 vcc_hi, vcc_hi, 0
	global_load_dword v120, v109, vcc
	global_load_dword v121, v110, vcc
	global_load_dword v122, v111, vcc
	global_load_dword v123, v112, vcc
	global_load_dword v124, v113, vcc
	s_cmp_lg_u32 s64, 0
	s_cbranch_scc1 .Lcv_pfwait_2
	v_and_b32_e32 v106, 63, v204
	v_lshrrev_b32_e32 v107, 3, v106
	v_and_b32_e32 v108, 7, v106
	v_readfirstlane_b32 vcc_lo, v204
	s_nop 3
	s_lshr_b32 vcc_lo, vcc_lo, 6
	s_mul_i32 vcc_hi, s85, 7
	s_add_i32 vcc_lo, vcc_lo, vcc_hi
	s_add_i32 vcc_lo, vcc_lo, -1
	s_add_i32 vcc_lo, vcc_lo, 1792
	s_cmp_ge_u32 vcc_lo, 3520
	s_cbranch_scc1 .Lcv_2_0_n0
	s_sub_u32 vcc_lo, vcc_lo, 0
	v_mov_b32_e32 v113, vcc_lo
	v_mul_u32_u24_e32 v109, 0x5d18, v113
	v_lshrrev_b32_e32 v109, 22, v109
	v_mul_u32_u24_e32 v110, 0xb0, v109
	v_sub_u32_e32 v110, v113, v110
	v_lshlrev_b32_e32 v109, 6, v109
	v_lshl_add_u32 v109, v107, 3, v109
	v_lshlrev_b32_e32 v110, 5, v110
	v_lshl_add_u32 v110, v108, 2, v110
	v_mul_u32_u24_e32 v111, 0x5800, v109
	v_lshl_add_u32 v111, v110, 2, v111
	v_lshrrev_b32_e32 v112, 7, v110
	v_lshlrev_b32_e32 v112, 8, v112
	v_and_b32_e32 v113, 0x7f, v110
	v_add_u32_e32 v112, v112, v113
	v_lshlrev_b32_e32 v112, 12, v112
	v_lshl_add_u32 v112, v109, 1, v112
	v_lshlrev_b32_e32 v113, 2, v109
	v_readlane_b32 vcc_lo, v250, 28
	v_readlane_b32 vcc_hi, v250, 29
	s_nop 4
	global_load_dwordx4 v[98:101], v113, vcc
	global_load_dwordx4 v[102:105], v113, vcc offset:16
	v_readlane_b32 vcc_lo, v250, 30
	v_readlane_b32 vcc_hi, v250, 31
	s_nop 4
	global_load_dwordx4 v[66:69], v111, vcc nt
	v_add_u32_e32 v111, 0x5800, v111
	global_load_dwordx4 v[70:73], v111, vcc nt
	v_add_u32_e32 v111, 0x5800, v111
	global_load_dwordx4 v[74:77], v111, vcc nt
	v_add_u32_e32 v111, 0x5800, v111
	global_load_dwordx4 v[78:81], v111, vcc nt
	v_add_u32_e32 v111, 0x5800, v111
	global_load_dwordx4 v[82:85], v111, vcc nt
	v_add_u32_e32 v111, 0x5800, v111
	global_load_dwordx4 v[86:89], v111, vcc nt
	v_add_u32_e32 v111, 0x5800, v111
	global_load_dwordx4 v[90:93], v111, vcc nt
	v_add_u32_e32 v111, 0x5800, v111
	global_load_dwordx4 v[94:97], v111, vcc nt
	v_readlane_b32 vcc_lo, v250, 36
	v_readlane_b32 vcc_hi, v250, 37
	s_nop 3
	s_add_u32 vcc_lo, vcc_lo, 0x5dc0000
	s_addc_u32 vcc_hi, vcc_hi, 0
	s_waitcnt vmcnt(0)
	v_mul_f32_e32 v66, v66, v98
	v_mul_f32_e32 v67, v67, v98
	v_mul_f32_e32 v68, v68, v98
	v_mul_f32_e32 v69, v69, v98
	v_mul_f32_e32 v70, v70, v99
	v_mul_f32_e32 v71, v71, v99
	v_mul_f32_e32 v72, v72, v99
	v_mul_f32_e32 v73, v73, v99
	v_mul_f32_e32 v74, v74, v100
	v_mul_f32_e32 v75, v75, v100
	v_mul_f32_e32 v76, v76, v100
	v_mul_f32_e32 v77, v77, v100
	v_mul_f32_e32 v78, v78, v101
	v_mul_f32_e32 v79, v79, v101
	v_mul_f32_e32 v80, v80, v101
	v_mul_f32_e32 v81, v81, v101
	v_mul_f32_e32 v82, v82, v102
	v_mul_f32_e32 v83, v83, v102
	v_mul_f32_e32 v84, v84, v102
	v_mul_f32_e32 v85, v85, v102
	v_mul_f32_e32 v86, v86, v103
	v_mul_f32_e32 v87, v87, v103
	v_mul_f32_e32 v88, v88, v103
	v_mul_f32_e32 v89, v89, v103
	v_mul_f32_e32 v90, v90, v104
	v_mul_f32_e32 v91, v91, v104
	v_mul_f32_e32 v92, v92, v104
	v_mul_f32_e32 v93, v93, v104
	v_mul_f32_e32 v94, v94, v105
	v_mul_f32_e32 v95, v95, v105
	v_mul_f32_e32 v96, v96, v105
	v_mul_f32_e32 v97, v97, v105
	v_cvt_pk_bf16_f32 v114, v66, v70
	v_cvt_pk_bf16_f32 v115, v74, v78
	v_cvt_pk_bf16_f32 v116, v82, v86
	v_cvt_pk_bf16_f32 v117, v90, v94
	v_cvt_pk_bf16_f32 v118, v67, v71
	v_cvt_pk_bf16_f32 v119, v75, v79
	v_cvt_pk_bf16_f32 v120, v83, v87
	v_cvt_pk_bf16_f32 v121, v91, v95
	v_cvt_pk_bf16_f32 v122, v68, v72
	v_cvt_pk_bf16_f32 v123, v76, v80
	v_cvt_pk_bf16_f32 v124, v84, v88
	v_cvt_pk_bf16_f32 v125, v92, v96
	v_cvt_pk_bf16_f32 v126, v69, v73
	v_cvt_pk_bf16_f32 v127, v77, v81
	v_cvt_pk_bf16_f32 v128, v85, v89
	v_cvt_pk_bf16_f32 v129, v93, v97
	global_store_dwordx4 v112, v[114:117], vcc sc1
	v_add_u32_e32 v112, 0x1000, v112
	global_store_dwordx4 v112, v[118:121], vcc sc1
	v_add_u32_e32 v112, 0x1000, v112
	global_store_dwordx4 v112, v[122:125], vcc sc1
	v_add_u32_e32 v112, 0x1000, v112
	global_store_dwordx4 v112, v[126:129], vcc sc1
	s_branch .Lcv_done_2_0

.Lcv_pfwait_2:
	s_waitcnt vmcnt(0)
.Lcv_skip_2:
	s_mov_b64 s[0:1], 0
	s_waitcnt lgkmcnt(0)
	s_barrier

; __device__ __forceinline__ unsigned cvt_pk_bf16(float lo, float hi) { unsigned r; asm volatile("v_cvt_pk_bf16_f32 %0, %1, %2" : "=v"(r) : "v"(lo), "v"(hi)); return r; }
; __device__ __forceinline__ void st16_wt(void* p, u32x4 v) { asm volatile("global_store_dwordx4 %0, %1, off sc1\n\ts_nop 1" :: "v"(p), "v"(v) : "memory"); }
; __device__ __forceinline__ void tr_item(const float* __restrict__ W, int K, int N, bf16_t* WT, const float* __restrict__ kscale, int rowmode, int item, int lane) {
;     const int nblk = N >> 5, kb = item / nblk, nb = item - kb * nblk;
;     const int c = lane >> 3, q = lane & 7, k0 = kb * 64 + c * 8, n0 = nb * 32 + q * 4;
;     f32x4 v[8];
; #pragma unroll
;     for (int i = 0; i < 8; ++i) v[i] = __builtin_nontemporal_load((const f32x4*)(W + (size_t)(k0 + i) * N + n0));
;     if (kscale) { const f32x4 s0 = *(const f32x4*)(kscale + k0), s1 = *(const f32x4*)(kscale + k0 + 4);
; #pragma unroll
;         for (int i = 0; i < 4; ++i) { v[i] = v[i] * s0[i]; v[4 + i] = v[4 + i] * s1[i]; } }
;     int drow;
;     if (rowmode == 0) drow = n0;
;     else if (rowmode == 3) { const int g = n0 - pg8::C_GA; drow = g < 0 ? n0 : pg8::C_GA + (((g & 2047) >> 7) << 8) + ((g >> 11) << 7) + (g & 127); }
;     else drow = ((n0 >> 7) << 8) + (n0 & 127) + (rowmode == 2 ? 128 : 0);
; #pragma unroll
;     for (int e = 0; e < 4; ++e) { u32x4 o; o.x = cvt_pk_bf16(v[0][e], v[1][e]); o.y = cvt_pk_bf16(v[2][e], v[3][e]); o.z = cvt_pk_bf16(v[4][e], v[5][e]); o.w = cvt_pk_bf16(v[6][e], v[7][e]);
;         pg8::st16_wt(WT + (size_t)(drow + e) * K + k0, o); }
.LBB0_524:
	s_or_b64 exec, exec, s[0:1]
	v_readfirstlane_b32 vcc_lo, v204
	s_nop 3
	s_lshr_b32 vcc_lo, vcc_lo, 6
	s_cmp_eq_u32 vcc_lo, 0
	s_cbranch_scc1 .Lcv_skip_3
	s_lshr_b32 m0, s85, 5
	v_subrev_u32_e32 v106, 64, v204
	v_mov_b32_e32 v107, m0
	v_lshlrev_b32_e32 v107, 8, v107
	v_mov_b32_e32 v108, v106
	v_lshrrev_b32_e32 v109, 3, v108
	v_add_u32_e32 v109, v109, v107
	v_mul_u32_u24_e32 v109, 0x1000, v109
	v_and_b32_e32 v108, 7, v108
	v_lshl_add_u32 v109, v108, 6, v109
	v_add_u32_e32 v108, 448, v106
	v_lshrrev_b32_e32 v110, 3, v108
	v_add_u32_e32 v110, v110, v107
	v_mul_u32_u24_e32 v110, 0x1000, v110
	v_and_b32_e32 v108, 7, v108
	v_lshl_add_u32 v110, v108, 6, v110
	v_add_u32_e32 v108, 896, v106
	v_lshrrev_b32_e32 v111, 3, v108
	v_add_u32_e32 v111, v111, v107
	v_mul_u32_u24_e32 v111, 0x1000, v111
	v_and_b32_e32 v108, 7, v108
	v_lshl_add_u32 v111, v108, 6, v111
	v_add_u32_e32 v108, 1344, v106
	v_lshrrev_b32_e32 v112, 3, v108
	v_add_u32_e32 v112, v112, v107
	v_mul_u32_u24_e32 v112, 0x1000, v112
	v_and_b32_e32 v108, 7, v108
	v_lshl_add_u32 v112, v108, 6, v112
	v_add_u32_e32 v108, 1792, v106
	v_and_b32_e32 v108, 0x7ff, v108
	v_lshrrev_b32_e32 v113, 3, v108
	v_add_u32_e32 v113, v113, v107
	v_mul_u32_u24_e32 v113, 0x1000, v113
	v_and_b32_e32 v108, 7, v108
	v_lshl_add_u32 v113, v108, 6, v113
	v_readlane_b32 vcc_lo, v250, 36
	v_readlane_b32 vcc_hi, v250, 37
	s_nop 3
	s_add_u32 vcc_lo, vcc_lo, 0x4dc0000
	s_addc_u32 vcc_hi, vcc_hi, 0
	s_cmp_lg_u32 s64, 0
	s_cselect_b32 m0, 0x800000, 0
	s_add_u32 vcc_lo, vcc_lo, m0
	s_addc_u32 vcc_hi, vcc_hi, 0
	global_load_dword v120, v109, vcc
	global_load_dword v121, v110, vcc
	global_load_dword v122, v111, vcc
	global_load_dword v123, v112, vcc
	global_load_dword v124, v113, vcc
	s_cmp_lg_u32 s64, 0
	s_cbranch_scc1 .Lcv_pfwait_3
	v_and_b32_e32 v106, 63, v204
	v_lshrrev_b32_e32 v107, 3, v106
	v_and_b32_e32 v108, 7, v106
	v_readfirstlane_b32 vcc_lo, v204
	s_nop 3
	s_lshr_b32 vcc_lo, vcc_lo, 6
	s_mul_i32 vcc_hi, s85, 7
	s_add_i32 vcc_lo, vcc_lo, vcc_hi
	s_add_i32 vcc_lo, vcc_lo, -1
	s_add_i32 vcc_lo, vcc_lo, 3584
	s_sub_u32 vcc_lo, vcc_lo, 3520
	v_mov_b32_e32 v113, vcc_lo
	v_mul_u32_u24_e32 v109, 0x5d18, v113
	v_lshrrev_b32_e32 v109, 22, v109
	v_mul_u32_u24_e32 v110, 0xb0, v109
	v_sub_u32_e32 v110, v113, v110
	v_lshlrev_b32_e32 v109, 6, v109
	v_lshl_add_u32 v109, v107, 3, v109
	v_lshlrev_b32_e32 v110, 5, v110
	v_lshl_add_u32 v110, v108, 2, v110
	v_mul_u32_u24_e32 v111, 0x5800, v109
	v_lshl_add_u32 v111, v110, 2, v111
	v_add_u32_e32 v111, 0x2c00000, v111
	v_lshrrev_b32_e32 v112, 7, v110
	v_lshlrev_b32_e32 v112, 8, v112
	v_and_b32_e32 v113, 0x7f, v110
	v_add_u32_e32 v112, v112, v113
	v_lshlrev_b32_e32 v112, 12, v112
	v_lshl_add_u32 v112, v109, 1, v112
	v_lshlrev_b32_e32 v113, 2, v109
	v_add_u32_e32 v113, 0x2000, v113
	v_readlane_b32 vcc_lo, v250, 28
	v_readlane_b32 vcc_hi, v250, 29
	s_nop 4
	global_load_dwordx4 v[98:101], v113, vcc
	global_load_dwordx4 v[102:105], v113, vcc offset:16
	v_readlane_b32 vcc_lo, v250, 30
	v_readlane_b32 vcc_hi, v250, 31
	s_nop 4
	global_load_dwordx4 v[66:69], v111, vcc nt
	v_add_u32_e32 v111, 0x5800, v111
	global_load_dwordx4 v[70:73], v111, vcc nt
	v_add_u32_e32 v111, 0x5800, v111
	global_load_dwordx4 v[74:77], v111, vcc nt
	v_add_u32_e32 v111, 0x5800, v111
	global_load_dwordx4 v[78:81], v111, vcc nt
	v_add_u32_e32 v111, 0x5800, v111
	global_load_dwordx4 v[82:85], v111, vcc nt
	v_add_u32_e32 v111, 0x5800, v111
	global_load_dwordx4 v[86:89], v111, vcc nt
	v_add_u32_e32 v111, 0x5800, v111
	global_load_dwordx4 v[90:93], v111, vcc nt
	v_add_u32_e32 v111, 0x5800, v111
	global_load_dwordx4 v[94:97], v111, vcc nt
	v_readlane_b32 vcc_lo, v250, 36
	v_readlane_b32 vcc_hi, v250, 37
	s_nop 3
	s_add_u32 vcc_lo, vcc_lo, 0x89c0000
	s_addc_u32 vcc_hi, vcc_hi, 0
	s_waitcnt vmcnt(0)
	v_mul_f32_e32 v66, v66, v98
	v_mul_f32_e32 v67, v67, v98
	v_mul_f32_e32 v68, v68, v98
	v_mul_f32_e32 v69, v69, v98
	v_mul_f32_e32 v70, v70, v99
	v_mul_f32_e32 v71, v71, v99
	v_mul_f32_e32 v72, v72, v99
	v_mul_f32_e32 v73, v73, v99
	v_mul_f32_e32 v74, v74, v100
	v_mul_f32_e32 v75, v75, v100
	v_mul_f32_e32 v76, v76, v100
	v_mul_f32_e32 v77, v77, v100
	v_mul_f32_e32 v78, v78, v101
	v_mul_f32_e32 v79, v79, v101
	v_mul_f32_e32 v80, v80, v101
	v_mul_f32_e32 v81, v81, v101
	v_mul_f32_e32 v82, v82, v102
	v_mul_f32_e32 v83, v83, v102
	v_mul_f32_e32 v84, v84, v102
	v_mul_f32_e32 v85, v85, v102
	v_mul_f32_e32 v86, v86, v103
	v_mul_f32_e32 v87, v87, v103
	v_mul_f32_e32 v88, v88, v103
	v_mul_f32_e32 v89, v89, v103
	v_mul_f32_e32 v90, v90, v104
	v_mul_f32_e32 v91, v91, v104
	v_mul_f32_e32 v92, v92, v104
	v_mul_f32_e32 v93, v93, v104
	v_mul_f32_e32 v94, v94, v105
	v_mul_f32_e32 v95, v95, v105
	v_mul_f32_e32 v96, v96, v105
	v_mul_f32_e32 v97, v97, v105
	v_cvt_pk_bf16_f32 v114, v66, v70
	v_cvt_pk_bf16_f32 v115, v74, v78
	v_cvt_pk_bf16_f32 v116, v82, v86
	v_cvt_pk_bf16_f32 v117, v90, v94
	v_cvt_pk_bf16_f32 v118, v67, v71
	v_cvt_pk_bf16_f32 v119, v75, v79
	v_cvt_pk_bf16_f32 v120, v83, v87
	v_cvt_pk_bf16_f32 v121, v91, v95
	v_cvt_pk_bf16_f32 v122, v68, v72
	v_cvt_pk_bf16_f32 v123, v76, v80
	v_cvt_pk_bf16_f32 v124, v84, v88
	v_cvt_pk_bf16_f32 v125, v92, v96
	v_cvt_pk_bf16_f32 v126, v69, v73
	v_cvt_pk_bf16_f32 v127, v77, v81
	v_cvt_pk_bf16_f32 v128, v85, v89
	v_cvt_pk_bf16_f32 v129, v93, v97
	global_store_dwordx4 v112, v[114:117], vcc sc1
	v_add_u32_e32 v112, 0x1000, v112
	global_store_dwordx4 v112, v[118:121], vcc sc1
	v_add_u32_e32 v112, 0x1000, v112
	global_store_dwordx4 v112, v[122:125], vcc sc1
	v_add_u32_e32 v112, 0x1000, v112
	global_store_dwordx4 v112, v[126:129], vcc sc1

.Lcv_pfwait_3:
	s_waitcnt vmcnt(0)
.Lcv_skip_3:
	s_mov_b64 s[0:1], 0
	s_waitcnt lgkmcnt(0)
	s_barrier

; __device__ __forceinline__ unsigned cvt_pk_bf16(float lo, float hi) { unsigned r; asm volatile("v_cvt_pk_bf16_f32 %0, %1, %2" : "=v"(r) : "v"(lo), "v"(hi)); return r; }
; __device__ __forceinline__ void st16_wt(void* p, u32x4 v) { asm volatile("global_store_dwordx4 %0, %1, off sc1\n\ts_nop 1" :: "v"(p), "v"(v) : "memory"); }
; __device__ __forceinline__ void tr_item(const float* __restrict__ W, int K, int N, bf16_t* WT, const float* __restrict__ kscale, int rowmode, int item, int lane) {
;     const int nblk = N >> 5, kb = item / nblk, nb = item - kb * nblk;
;     const int c = lane >> 3, q = lane & 7, k0 = kb * 64 + c * 8, n0 = nb * 32 + q * 4;
;     f32x4 v[8];
; #pragma unroll
;     for (int i = 0; i < 8; ++i) v[i] = __builtin_nontemporal_load((const f32x4*)(W + (size_t)(k0 + i) * N + n0));
;     if (kscale) { const f32x4 s0 = *(const f32x4*)(kscale + k0), s1 = *(const f32x4*)(kscale + k0 + 4);
; #pragma unroll
;         for (int i = 0; i < 4; ++i) { v[i] = v[i] * s0[i]; v[4 + i] = v[4 + i] * s1[i]; } }
;     int drow;
;     if (rowmode == 0) drow = n0;
;     else if (rowmode == 3) { const int g = n0 - pg8::C_GA; drow = g < 0 ? n0 : pg8::C_GA + (((g & 2047) >> 7) << 8) + ((g >> 11) << 7) + (g & 127); }
;     else drow = ((n0 >> 7) << 8) + (n0 & 127) + (rowmode == 2 ? 128 : 0);
; #pragma unroll
;     for (int e = 0; e < 4; ++e) { u32x4 o; o.x = cvt_pk_bf16(v[0][e], v[1][e]); o.y = cvt_pk_bf16(v[2][e], v[3][e]); o.z = cvt_pk_bf16(v[4][e], v[5][e]); o.w = cvt_pk_bf16(v[6][e], v[7][e]);
;         pg8::st16_wt(WT + (size_t)(drow + e) * K + k0, o); }
.LBB0_632:
	s_or_b64 exec, exec, s[0:1]
	v_readfirstlane_b32 vcc_lo, v204
	s_nop 3
	s_lshr_b32 vcc_lo, vcc_lo, 6
	s_cmp_eq_u32 vcc_lo, 0
	s_cbranch_scc1 .Lcv_skip_4
	s_lshr_b32 m0, s85, 5
	v_subrev_u32_e32 v106, 64, v204
	v_mov_b32_e32 v107, m0
	v_lshlrev_b32_e32 v107, 8, v107
	v_mov_b32_e32 v108, v106
	v_lshrrev_b32_e32 v109, 3, v108
	v_add_u32_e32 v109, v109, v107
	v_mul_u32_u24_e32 v109, 0x1000, v109
	v_and_b32_e32 v108, 7, v108
	v_lshl_add_u32 v109, v108, 6, v109
	v_add_u32_e32 v108, 448, v106
	v_lshrrev_b32_e32 v110, 3, v108
	v_add_u32_e32 v110, v110, v107
	v_mul_u32_u24_e32 v110, 0x1000, v110
	v_and_b32_e32 v108, 7, v108
	v_lshl_add_u32 v110, v108, 6, v110
	v_add_u32_e32 v108, 896, v106
	v_lshrrev_b32_e32 v111, 3, v108
	v_add_u32_e32 v111, v111, v107
	v_mul_u32_u24_e32 v111, 0x1000, v111
	v_and_b32_e32 v108, 7, v108
	v_lshl_add_u32 v111, v108, 6, v111
	v_add_u32_e32 v108, 1344, v106
	v_lshrrev_b32_e32 v112, 3, v108
	v_add_u32_e32 v112, v112, v107
	v_mul_u32_u24_e32 v112, 0x1000, v112
	v_and_b32_e32 v108, 7, v108
	v_lshl_add_u32 v112, v108, 6, v112
	v_add_u32_e32 v108, 1792, v106
	v_and_b32_e32 v108, 0x7ff, v108
	v_lshrrev_b32_e32 v113, 3, v108
	v_add_u32_e32 v113, v113, v107
	v_mul_u32_u24_e32 v113, 0x1000, v113
	v_and_b32_e32 v108, 7, v108
	v_lshl_add_u32 v113, v108, 6, v113
	v_readlane_b32 vcc_lo, v250, 36
	v_readlane_b32 vcc_hi, v250, 37
	s_nop 3
	s_add_u32 vcc_lo, vcc_lo, 0x5dc0000
	s_addc_u32 vcc_hi, vcc_hi, 0
	s_cmp_lg_u32 s64, 0
	s_cselect_b32 m0, 0x2c00000, 0
	s_add_u32 vcc_lo, vcc_lo, m0
	s_addc_u32 vcc_hi, vcc_hi, 0
	global_load_dword v120, v109, vcc
	global_load_dword v121, v110, vcc
	global_load_dword v122, v111, vcc
	global_load_dword v123, v112, vcc
	global_load_dword v124, v113, vcc
	s_cmp_lg_u32 s64, 0
	s_cbranch_scc1 .Lcv_pfwait_4
	v_and_b32_e32 v106, 63, v204
	v_lshrrev_b32_e32 v107, 3, v106
	v_and_b32_e32 v108, 7, v106
	v_readfirstlane_b32 vcc_lo, v204
	s_nop 3
	s_lshr_b32 vcc_lo, vcc_lo, 6
	s_mul_i32 vcc_hi, s85, 7
	s_add_i32 vcc_lo, vcc_lo, vcc_hi
	s_add_i32 vcc_lo, vcc_lo, -1
	s_cmp_ge_u32 vcc_lo, 1664
	s_cbranch_scc1 .Lcv_pfwait_4
	s_add_i32 vcc_lo, vcc_lo, 5376
	s_sub_u32 vcc_lo, vcc_lo, 3520
	v_mov_b32_e32 v113, vcc_lo
	v_mul_u32_u24_e32 v109, 0x5d18, v113
	v_lshrrev_b32_e32 v109, 22, v109
	v_mul_u32_u24_e32 v110, 0xb0, v109
	v_sub_u32_e32 v110, v113, v110
	v_lshlrev_b32_e32 v109, 6, v109
	v_lshl_add_u32 v109, v107, 3, v109
	v_lshlrev_b32_e32 v110, 5, v110
	v_lshl_add_u32 v110, v108, 2, v110
	v_mul_u32_u24_e32 v111, 0x5800, v109
	v_lshl_add_u32 v111, v110, 2, v111
	v_add_u32_e32 v111, 0x2c00000, v111
	v_lshrrev_b32_e32 v112, 7, v110
	v_lshlrev_b32_e32 v112, 8, v112
	v_and_b32_e32 v113, 0x7f, v110
	v_add_u32_e32 v112, v112, v113
	v_lshlrev_b32_e32 v112, 12, v112
	v_lshl_add_u32 v112, v109, 1, v112
	v_lshlrev_b32_e32 v113, 2, v109
	v_add_u32_e32 v113, 0x2000, v113
	v_readlane_b32 vcc_lo, v250, 28
	v_readlane_b32 vcc_hi, v250, 29
	s_nop 4
	global_load_dwordx4 v[98:101], v113, vcc
	global_load_dwordx4 v[102:105], v113, vcc offset:16
	v_readlane_b32 vcc_lo, v250, 30
	v_readlane_b32 vcc_hi, v250, 31
	s_nop 4
	global_load_dwordx4 v[66:69], v111, vcc nt
	v_add_u32_e32 v111, 0x5800, v111
	global_load_dwordx4 v[70:73], v111, vcc nt
	v_add_u32_e32 v111, 0x5800, v111
	global_load_dwordx4 v[74:77], v111, vcc nt
	v_add_u32_e32 v111, 0x5800, v111
	global_load_dwordx4 v[78:81], v111, vcc nt
	v_add_u32_e32 v111, 0x5800, v111
	global_load_dwordx4 v[82:85], v111, vcc nt
	v_add_u32_e32 v111, 0x5800, v111
	global_load_dwordx4 v[86:89], v111, vcc nt
	v_add_u32_e32 v111, 0x5800, v111
	global_load_dwordx4 v[90:93], v111, vcc nt
	v_add_u32_e32 v111, 0x5800, v111
	global_load_dwordx4 v[94:97], v111, vcc nt
	v_readlane_b32 vcc_lo, v250, 36
	v_readlane_b32 vcc_hi, v250, 37
	s_nop 3
	s_add_u32 vcc_lo, vcc_lo, 0x89c0000
	s_addc_u32 vcc_hi, vcc_hi, 0
	s_waitcnt vmcnt(0)
	v_mul_f32_e32 v66, v66, v98
	v_mul_f32_e32 v67, v67, v98
	v_mul_f32_e32 v68, v68, v98
	v_mul_f32_e32 v69, v69, v98
	v_mul_f32_e32 v70, v70, v99
	v_mul_f32_e32 v71, v71, v99
	v_mul_f32_e32 v72, v72, v99
	v_mul_f32_e32 v73, v73, v99
	v_mul_f32_e32 v74, v74, v100
	v_mul_f32_e32 v75, v75, v100
	v_mul_f32_e32 v76, v76, v100
	v_mul_f32_e32 v77, v77, v100
	v_mul_f32_e32 v78, v78, v101
	v_mul_f32_e32 v79, v79, v101
	v_mul_f32_e32 v80, v80, v101
	v_mul_f32_e32 v81, v81, v101
	v_mul_f32_e32 v82, v82, v102
	v_mul_f32_e32 v83, v83, v102
	v_mul_f32_e32 v84, v84, v102
	v_mul_f32_e32 v85, v85, v102
	v_mul_f32_e32 v86, v86, v103
	v_mul_f32_e32 v87, v87, v103
	v_mul_f32_e32 v88, v88, v103
	v_mul_f32_e32 v89, v89, v103
	v_mul_f32_e32 v90, v90, v104
	v_mul_f32_e32 v91, v91, v104
	v_mul_f32_e32 v92, v92, v104
	v_mul_f32_e32 v93, v93, v104
	v_mul_f32_e32 v94, v94, v105
	v_mul_f32_e32 v95, v95, v105
	v_mul_f32_e32 v96, v96, v105
	v_mul_f32_e32 v97, v97, v105
	v_cvt_pk_bf16_f32 v114, v66, v70
	v_cvt_pk_bf16_f32 v115, v74, v78
	v_cvt_pk_bf16_f32 v116, v82, v86
	v_cvt_pk_bf16_f32 v117, v90, v94
	v_cvt_pk_bf16_f32 v118, v67, v71
	v_cvt_pk_bf16_f32 v119, v75, v79
	v_cvt_pk_bf16_f32 v120, v83, v87
	v_cvt_pk_bf16_f32 v121, v91, v95
	v_cvt_pk_bf16_f32 v122, v68, v72
	v_cvt_pk_bf16_f32 v123, v76, v80
	v_cvt_pk_bf16_f32 v124, v84, v88
	v_cvt_pk_bf16_f32 v125, v92, v96
	v_cvt_pk_bf16_f32 v126, v69, v73
	v_cvt_pk_bf16_f32 v127, v77, v81
	v_cvt_pk_bf16_f32 v128, v85, v89
	v_cvt_pk_bf16_f32 v129, v93, v97
	global_store_dwordx4 v112, v[114:117], vcc sc1
	v_add_u32_e32 v112, 0x1000, v112
	global_store_dwordx4 v112, v[118:121], vcc sc1
	v_add_u32_e32 v112, 0x1000, v112
	global_store_dwordx4 v112, v[122:125], vcc sc1
	v_add_u32_e32 v112, 0x1000, v112
	global_store_dwordx4 v112, v[126:129], vcc sc1

.Lcv_pfwait_4:
	s_waitcnt vmcnt(0)
.Lcv_skip_4:
	s_mov_b64 s[0:1], 0
	s_waitcnt lgkmcnt(0)
	s_barrier

; __device__ __forceinline__ void xcd_barrier(const XcdBarrier& b) {
;     asm volatile("s_waitcnt vmcnt(0)" ::: "memory");
;     __syncthreads();
.LBB0_770:
	s_or_b64 exec, exec, s[0:1]
	v_readfirstlane_b32 vcc_lo, v204
	s_nop 3
	s_lshr_b32 vcc_lo, vcc_lo, 6
	s_cmp_eq_u32 vcc_lo, 0
	s_cbranch_scc1 .Lcv_skip_5
	s_lshr_b32 m0, s85, 5
	v_subrev_u32_e32 v106, 64, v204
	v_mov_b32_e32 v107, m0
	v_lshlrev_b32_e32 v107, 8, v107
	v_mov_b32_e32 v108, v106
	v_lshrrev_b32_e32 v109, 3, v108
	v_add_u32_e32 v109, v109, v107
	v_mul_u32_u24_e32 v109, 0x2c00, v109
	v_and_b32_e32 v108, 7, v108
	v_lshl_add_u32 v109, v108, 6, v109
	v_add_u32_e32 v108, 448, v106
	v_lshrrev_b32_e32 v110, 3, v108
	v_add_u32_e32 v110, v110, v107
	v_mul_u32_u24_e32 v110, 0x2c00, v110
	v_and_b32_e32 v108, 7, v108
	v_lshl_add_u32 v110, v108, 6, v110
	v_add_u32_e32 v108, 896, v106
	v_lshrrev_b32_e32 v111, 3, v108
	v_add_u32_e32 v111, v111, v107
	v_mul_u32_u24_e32 v111, 0x2c00, v111
	v_and_b32_e32 v108, 7, v108
	v_lshl_add_u32 v111, v108, 6, v111
	v_add_u32_e32 v108, 1344, v106
	v_lshrrev_b32_e32 v112, 3, v108
	v_add_u32_e32 v112, v112, v107
	v_mul_u32_u24_e32 v112, 0x2c00, v112
	v_and_b32_e32 v108, 7, v108
	v_lshl_add_u32 v112, v108, 6, v112
	v_add_u32_e32 v108, 1792, v106
	v_and_b32_e32 v108, 0x7ff, v108
	v_lshrrev_b32_e32 v113, 3, v108
	v_add_u32_e32 v113, v113, v107
	v_mul_u32_u24_e32 v113, 0x2c00, v113
	v_and_b32_e32 v108, 7, v108
	v_lshl_add_u32 v113, v108, 6, v113
	v_readlane_b32 vcc_lo, v250, 36
	v_readlane_b32 vcc_hi, v250, 37
	s_nop 3
	s_add_u32 vcc_lo, vcc_lo, 0xb5c0000
	s_addc_u32 vcc_hi, vcc_hi, 0
	s_cmp_lg_u32 s64, 0
	s_cselect_b32 m0, 0x1600000, 0
	s_add_u32 vcc_lo, vcc_lo, m0
	s_addc_u32 vcc_hi, vcc_hi, 0
	global_load_dword v120, v109, vcc
	global_load_dword v121, v110, vcc
	global_load_dword v122, v111, vcc
	global_load_dword v123, v112, vcc
	global_load_dword v124, v113, vcc
.Lcv_pfwait_5:
	s_waitcnt vmcnt(0)
.Lcv_skip_5:
	s_mov_b64 s[0:1], 0
	s_waitcnt lgkmcnt(0)
	s_barrier
.LBB0_771:
	s_and_b64 vcc, exec, s[0:1]
	s_cbranch_vccz .LBB0_783
	s_waitcnt vmcnt(0) lgkmcnt(0)
	s_barrier
	s_mov_b64 s[0:1], exec
	v_readlane_b32 s16, v248, 50
	v_readlane_b32 s17, v248, 51
	s_and_b64 s[16:17], s[0:1], s[16:17]
	s_mov_b64 exec, s[16:17]
	s_cbranch_execz .LBB0_782
	v_readlane_b32 s16, v250, 0
	v_readlane_b32 s17, v250, 1
	buffer_wbl2 sc1
	s_load_dwordx2 s[16:17], s[16:17], 0x58
	s_mov_b64 s[18:19], exec
	v_mbcnt_lo_u32_b32 v2, s18, 0
	v_mbcnt_hi_u32_b32 v2, s19, v2
	v_cmp_eq_u32_e32 vcc, 0, v2
	s_waitcnt lgkmcnt(0)
	global_load_dword v0, v1, s[16:17] offset:40
	s_and_saveexec_b64 s[20:21], vcc
	s_cbranch_execz .LBB0_775
	s_bcnt1_i32_b64 s4, s[18:19]
	v_mov_b32_e32 v3, s4
	global_atomic_add v3, v1, v3, s[16:17] offset:32 sc0

; __global__ void __launch_bounds__(NTHREADS, 2) mk_fwd(Args args) {
;     ...
; #pragma unroll 1
;     for (int l = 0; l < DEPTH; ++l) {
.LBB0_961:
	s_or_b64 exec, exec, s[0:1]
	v_readfirstlane_b32 vcc_lo, v204
	s_nop 3
	s_lshr_b32 vcc_lo, vcc_lo, 6
	s_cmp_eq_u32 vcc_lo, 0
	s_cbranch_scc1 .Lcv_skip_6
	s_cmp_lg_u32 s64, 0
	s_cbranch_scc1 .Lcv_skip_6
	s_lshr_b32 m0, s85, 5
	v_subrev_u32_e32 v106, 64, v204
	v_mov_b32_e32 v107, m0
	v_lshlrev_b32_e32 v107, 8, v107
	v_mov_b32_e32 v108, v106
	v_lshrrev_b32_e32 v109, 3, v108
	v_add_u32_e32 v109, v109, v107
	v_mul_u32_u24_e32 v109, 0x1000, v109
	v_and_b32_e32 v108, 7, v108
	v_lshl_add_u32 v109, v108, 6, v109
	v_add_u32_e32 v108, 448, v106
	v_lshrrev_b32_e32 v110, 3, v108
	v_add_u32_e32 v110, v110, v107
	v_mul_u32_u24_e32 v110, 0x1000, v110
	v_and_b32_e32 v108, 7, v108
	v_lshl_add_u32 v110, v108, 6, v110
	v_add_u32_e32 v108, 896, v106
	v_lshrrev_b32_e32 v111, 3, v108
	v_add_u32_e32 v111, v111, v107
	v_mul_u32_u24_e32 v111, 0x1000, v111
	v_and_b32_e32 v108, 7, v108
	v_lshl_add_u32 v111, v108, 6, v111
	v_add_u32_e32 v108, 1344, v106
	v_lshrrev_b32_e32 v112, 3, v108
	v_add_u32_e32 v112, v112, v107
	v_mul_u32_u24_e32 v112, 0x1000, v112
	v_and_b32_e32 v108, 7, v108
	v_lshl_add_u32 v112, v108, 6, v112
	v_add_u32_e32 v108, 1792, v106
	v_and_b32_e32 v108, 0x7ff, v108
	v_lshrrev_b32_e32 v113, 3, v108
	v_add_u32_e32 v113, v113, v107
	v_mul_u32_u24_e32 v113, 0x1000, v113
	v_and_b32_e32 v108, 7, v108
	v_lshl_add_u32 v113, v108, 6, v113
	v_readlane_b32 vcc_lo, v250, 36
	v_readlane_b32 vcc_hi, v250, 37
	s_nop 3
	s_add_u32 vcc_lo, vcc_lo, 0x1fc0000
	s_addc_u32 vcc_hi, vcc_hi, 0
	global_load_dword v120, v109, vcc
	global_load_dword v121, v110, vcc
	global_load_dword v122, v111, vcc
	global_load_dword v123, v112, vcc
	global_load_dword v124, v113, vcc
.Lcv_pfwait_6:
	s_waitcnt vmcnt(0)
.Lcv_skip_6:
	s_mov_b64 s[0:1], 0
	s_waitcnt lgkmcnt(0)
	s_barrier
.LBB0_962:
	s_and_b64 vcc, exec, s[0:1]
	s_cbranch_vccz .LBB0_149
	s_waitcnt vmcnt(0) lgkmcnt(0)
	s_barrier
	s_mov_b64 s[0:1], exec
	v_readlane_b32 s6, v248, 50
	v_readlane_b32 s7, v248, 51
	s_and_b64 s[6:7], s[0:1], s[6:7]
	s_mov_b64 exec, s[6:7]
	s_cbranch_execz .LBB0_148
	v_readlane_b32 s6, v250, 0
	v_readlane_b32 s7, v250, 1
	buffer_wbl2 sc1
	s_load_dwordx2 s[6:7], s[6:7], 0x58
	s_mov_b64 s[16:17], exec
	v_mbcnt_lo_u32_b32 v2, s16, 0
	v_mbcnt_hi_u32_b32 v2, s17, v2
	v_cmp_eq_u32_e32 vcc, 0, v2
	s_waitcnt lgkmcnt(0)
	global_load_dword v0, v1, s[6:7] offset:40
	s_and_saveexec_b64 s[18:19], vcc
	s_cbranch_execz .LBB0_966
	s_bcnt1_i32_b64 s2, s[16:17]
	v_mov_b32_e32 v3, s2
	global_atomic_add v3, v1, v3, s[6:7] offset:32 sc0
